# as v47 plus B0 fragment LDS reads for the next K tile issued inside the preceding MFMA burst (registers dead after its 16th MFMA)
# baseline (speedup 1.0000x reference)
; #define PG8_STAGE(bufoff, gbase, voff) do { _Pragma("unroll") for (int _i = 0; _i < 2; ++_i) \
;         __builtin_amdgcn_global_load_lds((const unsigned*)((const char*)(gbase) + (voff)[_i]), (PG8_LAS unsigned*)(lds + (bufoff) + ldsw + _i * 8192), 16, 0, 0); } while (0)
; #define PG8_LDA(dst, b, h) do { _Pragma("unroll") for (int m = 0; m < 4; ++m) _Pragma("unroll") for (int k = 0; k < 2; ++k) dst[m][k] = *(const PG8_LAS bf16x8*)(lds + PG8_SA(b, h) + aoff + m * 2048 + k * 1024); } while (0)
; #define PG8_LDB(dst, b, h) do { _Pragma("unroll") for (int n = 0; n < 2; ++n) _Pragma("unroll") for (int k = 0; k < 2; ++k) dst[n][k] = *(const PG8_LAS bf16x8*)(lds + PG8_SB(b, h) + boff + n * 2048 + k * 1024); } while (0)
; #define PG8_MMA(ai, bj, At, Bt) do { __builtin_amdgcn_s_setprio(1); _Pragma("unroll") for (int m = 0; m < 4; ++m) _Pragma("unroll") for (int n = 0; n < 2; ++n) _Pragma("unroll") for (int k = 0; k < 2; ++k) \
;         acc[ai][bj][m][n] = __builtin_amdgcn_mfma_f32_16x16x32_bf16(Bt[n][k], At[m][k], acc[ai][bj][m][n], 0, 0, 0); __builtin_amdgcn_s_setprio(0); } while (0)
; #define PG8_WAIT_V(n) asm volatile("s_waitcnt vmcnt(" #n ")" ::: "memory")
; template <class Epi, class Sched, bool ALIGN_EPI = false, bool SP2 = false>
; __device__ __forceinline__ void gemm_phase(PG8_LAS unsigned char* lds, const Gemm g, const Sched& S, const Epi& E) {
;     ...
;         for (int t = 0; t < nt; t += 2) {
;             const bool last = (t == nt - 2);
;             const char* a1 = cA + (size_t)(t + 1) * kstep;
;             const char* a2 = last ? nA : cA + (size_t)(t + 2) * kstep; const char* b2 = last ? nB : cB + (size_t)(t + 2) * kstep;
;             const char* a3 = a2 + kstep; const char* b3 = b2 + kstep;
;             if (last && has_next) S.a_ready(nxt);
;             if constexpr (SP2) {
;             PG8_LDB(B0, 0, 0); PG8_LDB(B1, 0, 1); PG8_SCHED; PG8_LDA(At, 0, 0); PG8_STAGE(PG8_SA(1, 1), a1 + hstep, voffA);
;             PG8_WAIT_V(8); PG8_WAIT_L(0); PG8_BAR; PG8_MMA(0, 0, At, B0); PG8_MMA(0, 1, At, B1); PG8_BAR; PG8_SCHED;
;     ...
;         if (zero_acc) {
; #pragma unroll
;         for (int a = 0; a < 2; ++a)
; #pragma unroll
;             for (int b = 0; b < 2; ++b)
; #pragma unroll
;                 for (int m = 0; m < 4; ++m)
; #pragma unroll
;                     for (int n = 0; n < 2; ++n) acc[a][b][m][n] = (f32x4){0.f, 0.f, 0.f, 0.f};
.LBB0_300:
	s_ashr_i32 s13, s12, 31
	s_lshl_b64 s[28:29], s[12:13], 20
	s_add_u32 s28, s43, s28
	s_addc_u32 s29, s44, s29
	s_ashr_i32 s11, s10, 31
	s_lshl_b64 s[30:31], s[10:11], 20
	s_add_u32 s30, s45, s30
	s_addc_u32 s31, s46, s31
	s_and_b64 s[40:41], s[0:1], exec
	s_cselect_b32 s11, s29, s37
	s_cselect_b32 s13, s28, s36
	s_cselect_b32 s56, s31, s39
	s_cselect_b32 s57, s30, s38
	s_add_u32 s36, s36, 0x80080
	s_addc_u32 s37, s37, 0
	s_add_u32 s58, s38, 0x100
	v_mov_b32_e32 v4, 0
	s_addc_u32 s59, s39, 0
	s_mov_b32 s60, -2
	v_mov_b32_e32 v5, v4
	v_mov_b32_e32 v6, v4
	v_mov_b32_e32 v7, v4
	v_mov_b32_e32 v12, v4
	v_mov_b32_e32 v13, v4
	v_mov_b32_e32 v14, v4
	v_mov_b32_e32 v15, v4
	v_mov_b32_e32 v20, v4
	v_mov_b32_e32 v21, v4
	v_mov_b32_e32 v22, v4
	v_mov_b32_e32 v23, v4
	v_mov_b32_e32 v28, v4
	v_mov_b32_e32 v29, v4
	v_mov_b32_e32 v30, v4
	v_mov_b32_e32 v31, v4
	v_mov_b32_e32 v36, v4
	v_mov_b32_e32 v37, v4
	v_mov_b32_e32 v38, v4
	v_mov_b32_e32 v39, v4
	v_mov_b32_e32 v44, v4
	v_mov_b32_e32 v45, v4
	v_mov_b32_e32 v46, v4
	v_mov_b32_e32 v47, v4
	v_mov_b32_e32 v52, v4
	v_mov_b32_e32 v53, v4
	v_mov_b32_e32 v54, v4
	v_mov_b32_e32 v55, v4
	v_mov_b32_e32 v60, v4
	v_mov_b32_e32 v61, v4
	v_mov_b32_e32 v62, v4
	v_mov_b32_e32 v63, v4
	v_mov_b32_e32 v8, v4
	v_mov_b32_e32 v9, v4
	v_mov_b32_e32 v10, v4
	v_mov_b32_e32 v11, v4
	v_mov_b32_e32 v16, v4
	v_mov_b32_e32 v17, v4
	v_mov_b32_e32 v18, v4
	v_mov_b32_e32 v19, v4
	v_mov_b32_e32 v24, v4
	v_mov_b32_e32 v25, v4
	v_mov_b32_e32 v26, v4
	v_mov_b32_e32 v27, v4
	v_mov_b32_e32 v32, v4
	v_mov_b32_e32 v33, v4
	v_mov_b32_e32 v34, v4
	v_mov_b32_e32 v35, v4
	v_mov_b32_e32 v40, v4
	v_mov_b32_e32 v41, v4
	v_mov_b32_e32 v42, v4
	v_mov_b32_e32 v43, v4
	v_mov_b32_e32 v48, v4
	v_mov_b32_e32 v49, v4
	v_mov_b32_e32 v50, v4
	v_mov_b32_e32 v51, v4
	v_mov_b32_e32 v56, v4
	v_mov_b32_e32 v57, v4
	v_mov_b32_e32 v58, v4
	v_mov_b32_e32 v59, v4
	v_mov_b32_e32 v64, v4
	v_mov_b32_e32 v65, v4
	v_mov_b32_e32 v66, v4
	v_mov_b32_e32 v67, v4
	v_mov_b32_e32 v68, v4
	v_mov_b32_e32 v69, v4
	v_mov_b32_e32 v70, v4
	v_mov_b32_e32 v71, v4
	v_mov_b32_e32 v76, v4
	v_mov_b32_e32 v77, v4
	v_mov_b32_e32 v78, v4
	v_mov_b32_e32 v79, v4
	v_mov_b32_e32 v84, v4
	v_mov_b32_e32 v85, v4
	v_mov_b32_e32 v86, v4
	v_mov_b32_e32 v87, v4
	v_mov_b32_e32 v92, v4
	v_mov_b32_e32 v93, v4
	v_mov_b32_e32 v94, v4
	v_mov_b32_e32 v95, v4
	v_mov_b32_e32 v100, v4
	v_mov_b32_e32 v101, v4
	v_mov_b32_e32 v102, v4
	v_mov_b32_e32 v103, v4
	v_mov_b32_e32 v108, v4
	v_mov_b32_e32 v109, v4
	v_mov_b32_e32 v110, v4
	v_mov_b32_e32 v111, v4
	v_mov_b32_e32 v116, v4
	v_mov_b32_e32 v117, v4
	v_mov_b32_e32 v118, v4
	v_mov_b32_e32 v119, v4
	v_mov_b32_e32 v124, v4
	v_mov_b32_e32 v125, v4
	v_mov_b32_e32 v126, v4
	v_mov_b32_e32 v127, v4
	v_mov_b32_e32 v72, v4
	v_mov_b32_e32 v73, v4
	v_mov_b32_e32 v74, v4
	v_mov_b32_e32 v75, v4
	v_mov_b32_e32 v80, v4
	v_mov_b32_e32 v81, v4
	v_mov_b32_e32 v82, v4
	v_mov_b32_e32 v83, v4
	v_mov_b32_e32 v88, v4
	v_mov_b32_e32 v89, v4
	v_mov_b32_e32 v90, v4
	v_mov_b32_e32 v91, v4
	v_mov_b32_e32 v96, v4
	v_mov_b32_e32 v97, v4
	v_mov_b32_e32 v98, v4
	v_mov_b32_e32 v99, v4
	v_mov_b32_e32 v104, v4
	v_mov_b32_e32 v105, v4
	v_mov_b32_e32 v106, v4
	v_mov_b32_e32 v107, v4
	v_mov_b32_e32 v112, v4
	v_mov_b32_e32 v113, v4
	v_mov_b32_e32 v114, v4
	v_mov_b32_e32 v115, v4
	v_mov_b32_e32 v120, v4
	v_mov_b32_e32 v121, v4
	v_mov_b32_e32 v122, v4
	v_mov_b32_e32 v123, v4
	v_mov_b32_e32 v128, v4
	v_mov_b32_e32 v129, v4
	v_mov_b32_e32 v130, v4
	v_mov_b32_e32 v131, v4
	v_add_u32_e32 v249, 0x10000, v150
	ds_read_b128 v[142:145], v249
	ds_read_b128 v[146:149], v249 offset:1024
	ds_read_b128 v[154:157], v249 offset:2048
	ds_read_b128 v[158:161], v249 offset:3072
	.p2align 6
	s_nop 0
.LBB0_301:
	s_add_u32 s38, s36, 0xfff80080
	s_addc_u32 s39, s37, -1
	s_add_i32 s61, 0, 0x10000
	s_cmp_eq_u32 s60, 28
	s_cselect_b32 s41, s11, s39
	s_cselect_b32 s40, s13, s38
	s_cselect_b32 s39, s56, s59
	s_cselect_b32 s38, s57, s58
	s_add_i32 s64, 0, 0x14000
	ds_read_b128 v[174:177], v249 offset:16384
	ds_read_b128 v[178:181], v249 offset:17408
	ds_read_b128 v[204:207], v249 offset:18432
	ds_read_b128 v[208:211], v249 offset:19456
	s_add_i32 m0, s47, 0xc000
	ds_read_b128 v[212:215], v153
	ds_read_b128 v[216:219], v153 offset:1024
	ds_read_b128 v[220:223], v153 offset:2048
	ds_read_b128 v[224:227], v153 offset:3072
	ds_read_b128 v[228:231], v153 offset:4096
	ds_read_b128 v[232:235], v153 offset:5120
	ds_read_b128 v[236:239], v153 offset:6144
	ds_read_b128 v[240:243], v153 offset:7168
	global_load_lds_dwordx4 v138, s[36:37]
	s_add_i32 m0, s47, 0xe000
	s_nop 0
	global_load_lds_dwordx4 v140, s[36:37]
	s_nop 0
	s_waitcnt vmcnt(8) lgkmcnt(0)
	s_barrier
; #define PG8_STAGE(bufoff, gbase, voff) do { _Pragma("unroll") for (int _i = 0; _i < 2; ++_i) \
;         __builtin_amdgcn_global_load_lds((const unsigned*)((const char*)(gbase) + (voff)[_i]), (PG8_LAS unsigned*)(lds + (bufoff) + ldsw + _i * 8192), 16, 0, 0); } while (0)
; #define PG8_LDA(dst, b, h) do { _Pragma("unroll") for (int m = 0; m < 4; ++m) _Pragma("unroll") for (int k = 0; k < 2; ++k) dst[m][k] = *(const PG8_LAS bf16x8*)(lds + PG8_SA(b, h) + aoff + m * 2048 + k * 1024); } while (0)
; #define PG8_MMA(ai, bj, At, Bt) do { __builtin_amdgcn_s_setprio(1); _Pragma("unroll") for (int m = 0; m < 4; ++m) _Pragma("unroll") for (int n = 0; n < 2; ++n) _Pragma("unroll") for (int k = 0; k < 2; ++k) \
;         acc[ai][bj][m][n] = __builtin_amdgcn_mfma_f32_16x16x32_bf16(Bt[n][k], At[m][k], acc[ai][bj][m][n], 0, 0, 0); __builtin_amdgcn_s_setprio(0); } while (0)
; #define PG8_WAIT_V(n) asm volatile("s_waitcnt vmcnt(" #n ")" ::: "memory")
; #define PG8_WAIT_L(n) asm volatile("s_waitcnt lgkmcnt(" #n ")" ::: "memory")
; #define PG8_BAR __builtin_amdgcn_s_barrier()
; #define PG8_SCHED __builtin_amdgcn_sched_barrier(0)
; template <class Epi, class Sched, bool ALIGN_EPI = false, bool SP2 = false>
; __device__ __forceinline__ void gemm_phase(PG8_LAS unsigned char* lds, const Gemm g, const Sched& S, const Epi& E) {
;     ...
;             PG8_LDA(At, 0, 1); PG8_STAGE(PG8_SB(0, 0), b2, voffB); PG8_STAGE(PG8_SB(0, 1), b2 + hstep, voffB); PG8_STAGE(PG8_SA(0, 0), a2, voffA);
;             PG8_WAIT_V(8); PG8_WAIT_L(0); PG8_BAR; PG8_MMA(1, 0, At, B0); PG8_MMA(1, 1, At, B1); PG8_BAR; PG8_SCHED;
	s_setprio 0
	s_waitcnt lgkmcnt(0)
	v_mfma_f32_16x16x32_bf16 v[128:131], v[142:145], v[212:215], v[128:131]
	v_mfma_f32_16x16x32_bf16 v[120:123], v[154:157], v[212:215], v[120:123]
	v_mfma_f32_16x16x32_bf16 v[112:115], v[142:145], v[220:223], v[112:115]
	v_mfma_f32_16x16x32_bf16 v[104:107], v[154:157], v[220:223], v[104:107]
	v_mfma_f32_16x16x32_bf16 v[96:99], v[142:145], v[228:231], v[96:99]
	v_mfma_f32_16x16x32_bf16 v[88:91], v[154:157], v[228:231], v[88:91]
	v_mfma_f32_16x16x32_bf16 v[80:83], v[142:145], v[236:239], v[80:83]
	v_mfma_f32_16x16x32_bf16 v[72:75], v[154:157], v[236:239], v[72:75]
	v_mfma_f32_16x16x32_bf16 v[128:131], v[146:149], v[216:219], v[128:131]
	v_mfma_f32_16x16x32_bf16 v[120:123], v[158:161], v[216:219], v[120:123]
	v_mfma_f32_16x16x32_bf16 v[112:115], v[146:149], v[224:227], v[112:115]
	v_mfma_f32_16x16x32_bf16 v[104:107], v[158:161], v[224:227], v[104:107]
	v_mfma_f32_16x16x32_bf16 v[96:99], v[146:149], v[232:235], v[96:99]
	v_mfma_f32_16x16x32_bf16 v[88:91], v[158:161], v[232:235], v[88:91]
	v_mfma_f32_16x16x32_bf16 v[80:83], v[146:149], v[240:243], v[80:83]
	v_mfma_f32_16x16x32_bf16 v[72:75], v[158:161], v[240:243], v[72:75]
	v_mfma_f32_16x16x32_bf16 v[124:127], v[174:177], v[212:215], v[124:127]
	v_mfma_f32_16x16x32_bf16 v[116:119], v[204:207], v[212:215], v[116:119]
	v_mfma_f32_16x16x32_bf16 v[108:111], v[174:177], v[220:223], v[108:111]
	v_mfma_f32_16x16x32_bf16 v[100:103], v[204:207], v[220:223], v[100:103]
	v_mfma_f32_16x16x32_bf16 v[92:95], v[174:177], v[228:231], v[92:95]
	v_mfma_f32_16x16x32_bf16 v[84:87], v[204:207], v[228:231], v[84:87]
	v_mfma_f32_16x16x32_bf16 v[76:79], v[174:177], v[236:239], v[76:79]
	v_mfma_f32_16x16x32_bf16 v[68:71], v[204:207], v[236:239], v[68:71]
	v_mfma_f32_16x16x32_bf16 v[124:127], v[178:181], v[216:219], v[124:127]
	v_mfma_f32_16x16x32_bf16 v[116:119], v[208:211], v[216:219], v[116:119]
	v_mfma_f32_16x16x32_bf16 v[108:111], v[178:181], v[224:227], v[108:111]
	v_mfma_f32_16x16x32_bf16 v[100:103], v[208:211], v[224:227], v[100:103]
	v_mfma_f32_16x16x32_bf16 v[92:95], v[178:181], v[232:235], v[92:95]
	v_mfma_f32_16x16x32_bf16 v[84:87], v[208:211], v[232:235], v[84:87]
	v_mfma_f32_16x16x32_bf16 v[76:79], v[178:181], v[240:243], v[76:79]
	v_mfma_f32_16x16x32_bf16 v[68:71], v[208:211], v[240:243], v[68:71]
	s_setprio 3
	s_barrier
	s_add_i32 s61, s61, s42
	s_mov_b32 m0, s61
	ds_read_b128 v[212:215], v153 offset:16384
	ds_read_b128 v[216:219], v153 offset:17408
	ds_read_b128 v[220:223], v153 offset:18432
	ds_read_b128 v[224:227], v153 offset:19456
	ds_read_b128 v[228:231], v153 offset:20480
	ds_read_b128 v[232:235], v153 offset:21504
	ds_read_b128 v[236:239], v153 offset:22528
	ds_read_b128 v[240:243], v153 offset:23552
	global_load_lds_dwordx4 v2, s[38:39]
	s_add_i32 m0, s61, 0x2000
	s_add_u32 s62, s38, 0x80000
	s_addc_u32 s63, s39, 0
	s_add_i32 s61, s64, s42
	global_load_lds_dwordx4 v132, s[38:39]
	s_mov_b32 m0, s61
	s_nop 0
	global_load_lds_dwordx4 v2, s[62:63]
	s_add_i32 m0, s61, 0x2000
	s_nop 0
	global_load_lds_dwordx4 v132, s[62:63]
	s_mov_b32 m0, s47
	s_nop 0
	global_load_lds_dwordx4 v136, s[40:41]
	s_mov_b32 m0, s48
	s_nop 0
	global_load_lds_dwordx4 v134, s[40:41]
	s_nop 0
	s_waitcnt vmcnt(8) lgkmcnt(0)
	s_barrier
	s_setprio 0
	s_waitcnt lgkmcnt(0)
	v_mfma_f32_16x16x32_bf16 v[64:67], v[142:145], v[212:215], v[64:67]
	v_mfma_f32_16x16x32_bf16 v[56:59], v[154:157], v[212:215], v[56:59]
	v_mfma_f32_16x16x32_bf16 v[48:51], v[142:145], v[220:223], v[48:51]
	v_mfma_f32_16x16x32_bf16 v[40:43], v[154:157], v[220:223], v[40:43]
	v_mfma_f32_16x16x32_bf16 v[32:35], v[142:145], v[228:231], v[32:35]
	v_mfma_f32_16x16x32_bf16 v[24:27], v[154:157], v[228:231], v[24:27]
	v_mfma_f32_16x16x32_bf16 v[16:19], v[142:145], v[236:239], v[16:19]
	v_mfma_f32_16x16x32_bf16 v[8:11], v[154:157], v[236:239], v[8:11]
	v_mfma_f32_16x16x32_bf16 v[64:67], v[146:149], v[216:219], v[64:67]
	v_mfma_f32_16x16x32_bf16 v[56:59], v[158:161], v[216:219], v[56:59]
	v_mfma_f32_16x16x32_bf16 v[48:51], v[146:149], v[224:227], v[48:51]
	v_mfma_f32_16x16x32_bf16 v[40:43], v[158:161], v[224:227], v[40:43]
	v_mfma_f32_16x16x32_bf16 v[32:35], v[146:149], v[232:235], v[32:35]
	v_mfma_f32_16x16x32_bf16 v[24:27], v[158:161], v[232:235], v[24:27]
	v_mfma_f32_16x16x32_bf16 v[16:19], v[146:149], v[240:243], v[16:19]
	v_mfma_f32_16x16x32_bf16 v[8:11], v[158:161], v[240:243], v[8:11]
	v_mfma_f32_16x16x32_bf16 v[60:63], v[174:177], v[212:215], v[60:63]
	ds_read_b128 v[142:145], v249 offset:32768
	v_mfma_f32_16x16x32_bf16 v[52:55], v[204:207], v[212:215], v[52:55]
	ds_read_b128 v[146:149], v249 offset:33792
	v_mfma_f32_16x16x32_bf16 v[44:47], v[174:177], v[220:223], v[44:47]
	ds_read_b128 v[154:157], v249 offset:34816
	v_mfma_f32_16x16x32_bf16 v[36:39], v[204:207], v[220:223], v[36:39]
	ds_read_b128 v[158:161], v249 offset:35840
	v_mfma_f32_16x16x32_bf16 v[28:31], v[174:177], v[228:231], v[28:31]
	v_mfma_f32_16x16x32_bf16 v[20:23], v[204:207], v[228:231], v[20:23]
	v_mfma_f32_16x16x32_bf16 v[12:15], v[174:177], v[236:239], v[12:15]
	v_mfma_f32_16x16x32_bf16 v[4:7], v[204:207], v[236:239], v[4:7]
	v_mfma_f32_16x16x32_bf16 v[60:63], v[178:181], v[216:219], v[60:63]
	v_mfma_f32_16x16x32_bf16 v[52:55], v[208:211], v[216:219], v[52:55]
	v_mfma_f32_16x16x32_bf16 v[44:47], v[178:181], v[224:227], v[44:47]
	v_mfma_f32_16x16x32_bf16 v[36:39], v[208:211], v[224:227], v[36:39]
	v_mfma_f32_16x16x32_bf16 v[28:31], v[178:181], v[232:235], v[28:31]
	v_mfma_f32_16x16x32_bf16 v[20:23], v[208:211], v[232:235], v[20:23]
	v_mfma_f32_16x16x32_bf16 v[12:15], v[178:181], v[240:243], v[12:15]
	v_mfma_f32_16x16x32_bf16 v[4:7], v[208:211], v[240:243], v[4:7]
	s_setprio 3
	s_barrier
; #define PG8_STAGE(bufoff, gbase, voff) do { _Pragma("unroll") for (int _i = 0; _i < 2; ++_i) \
;         __builtin_amdgcn_global_load_lds((const unsigned*)((const char*)(gbase) + (voff)[_i]), (PG8_LAS unsigned*)(lds + (bufoff) + ldsw + _i * 8192), 16, 0, 0); } while (0)
; #define PG8_LDA(dst, b, h) do { _Pragma("unroll") for (int m = 0; m < 4; ++m) _Pragma("unroll") for (int k = 0; k < 2; ++k) dst[m][k] = *(const PG8_LAS bf16x8*)(lds + PG8_SA(b, h) + aoff + m * 2048 + k * 1024); } while (0)
; #define PG8_LDB(dst, b, h) do { _Pragma("unroll") for (int n = 0; n < 2; ++n) _Pragma("unroll") for (int k = 0; k < 2; ++k) dst[n][k] = *(const PG8_LAS bf16x8*)(lds + PG8_SB(b, h) + boff + n * 2048 + k * 1024); } while (0)
; #define PG8_MMA(ai, bj, At, Bt) do { __builtin_amdgcn_s_setprio(1); _Pragma("unroll") for (int m = 0; m < 4; ++m) _Pragma("unroll") for (int n = 0; n < 2; ++n) _Pragma("unroll") for (int k = 0; k < 2; ++k) \
;         acc[ai][bj][m][n] = __builtin_amdgcn_mfma_f32_16x16x32_bf16(Bt[n][k], At[m][k], acc[ai][bj][m][n], 0, 0, 0); __builtin_amdgcn_s_setprio(0); } while (0)
; #define PG8_WAIT_V(n) asm volatile("s_waitcnt vmcnt(" #n ")" ::: "memory")
; #define PG8_WAIT_L(n) asm volatile("s_waitcnt lgkmcnt(" #n ")" ::: "memory")
; #define PG8_BAR __builtin_amdgcn_s_barrier()
; #define PG8_SCHED __builtin_amdgcn_sched_barrier(0)
; template <class Epi, class Sched, bool ALIGN_EPI = false, bool SP2 = false>
; __device__ __forceinline__ void gemm_phase(PG8_LAS unsigned char* lds, const Gemm g, const Sched& S, const Epi& E) {
;     ...
;             PG8_LDB(B0, 1, 0); PG8_LDB(B1, 1, 1); PG8_SCHED; PG8_LDA(At, 1, 0); PG8_STAGE(PG8_SA(0, 1), a2 + hstep, voffA);
;             PG8_WAIT_V(8); PG8_WAIT_L(0); PG8_BAR; PG8_MMA(0, 0, At, B0); PG8_MMA(0, 1, At, B1); PG8_BAR; PG8_SCHED;
;             PG8_LDA(At, 1, 1); PG8_STAGE(PG8_SB(1, 0), b3, voffB); PG8_STAGE(PG8_SB(1, 1), b3 + hstep, voffB); PG8_STAGE(PG8_SA(1, 0), a3, voffA);
;             PG8_WAIT_V(8); PG8_WAIT_L(0); PG8_BAR; PG8_MMA(1, 0, At, B0); PG8_MMA(1, 1, At, B1); PG8_BAR; PG8_SCHED;
	s_add_i32 s61, 0, 0x18000
	s_add_i32 s62, 0, 0x1c000
	ds_read_b128 v[174:177], v249 offset:49152
	ds_read_b128 v[178:181], v249 offset:50176
	ds_read_b128 v[204:207], v249 offset:51200
	ds_read_b128 v[208:211], v249 offset:52224
	s_add_u32 s100, s40, 0x80
	s_addc_u32 s101, s41, 0
	s_add_u32 s40, s40, 0x80000
	s_addc_u32 s41, s41, 0
	s_mov_b32 m0, s49
	ds_read_b128 v[212:215], v153 offset:32768
	ds_read_b128 v[216:219], v153 offset:33792
	ds_read_b128 v[220:223], v153 offset:34816
	ds_read_b128 v[224:227], v153 offset:35840
	ds_read_b128 v[228:231], v153 offset:36864
	ds_read_b128 v[232:235], v153 offset:37888
	ds_read_b128 v[236:239], v153 offset:38912
	ds_read_b128 v[240:243], v153 offset:39936
	global_load_lds_dwordx4 v136, s[40:41]
	s_mov_b32 m0, s50
	s_nop 0
	global_load_lds_dwordx4 v134, s[40:41]
	s_nop 0
	s_waitcnt vmcnt(8) lgkmcnt(0)
	s_barrier
	s_setprio 0
	s_waitcnt lgkmcnt(0)
	v_mfma_f32_16x16x32_bf16 v[128:131], v[142:145], v[212:215], v[128:131]
	v_mfma_f32_16x16x32_bf16 v[120:123], v[154:157], v[212:215], v[120:123]
	v_mfma_f32_16x16x32_bf16 v[112:115], v[142:145], v[220:223], v[112:115]
	v_mfma_f32_16x16x32_bf16 v[104:107], v[154:157], v[220:223], v[104:107]
	v_mfma_f32_16x16x32_bf16 v[96:99], v[142:145], v[228:231], v[96:99]
	v_mfma_f32_16x16x32_bf16 v[88:91], v[154:157], v[228:231], v[88:91]
	v_mfma_f32_16x16x32_bf16 v[80:83], v[142:145], v[236:239], v[80:83]
	v_mfma_f32_16x16x32_bf16 v[72:75], v[154:157], v[236:239], v[72:75]
	v_mfma_f32_16x16x32_bf16 v[128:131], v[146:149], v[216:219], v[128:131]
	v_mfma_f32_16x16x32_bf16 v[120:123], v[158:161], v[216:219], v[120:123]
	v_mfma_f32_16x16x32_bf16 v[112:115], v[146:149], v[224:227], v[112:115]
	v_mfma_f32_16x16x32_bf16 v[104:107], v[158:161], v[224:227], v[104:107]
	v_mfma_f32_16x16x32_bf16 v[96:99], v[146:149], v[232:235], v[96:99]
	v_mfma_f32_16x16x32_bf16 v[88:91], v[158:161], v[232:235], v[88:91]
	v_mfma_f32_16x16x32_bf16 v[80:83], v[146:149], v[240:243], v[80:83]
	v_mfma_f32_16x16x32_bf16 v[72:75], v[158:161], v[240:243], v[72:75]
	v_mfma_f32_16x16x32_bf16 v[124:127], v[174:177], v[212:215], v[124:127]
	v_mfma_f32_16x16x32_bf16 v[116:119], v[204:207], v[212:215], v[116:119]
	v_mfma_f32_16x16x32_bf16 v[108:111], v[174:177], v[220:223], v[108:111]
	v_mfma_f32_16x16x32_bf16 v[100:103], v[204:207], v[220:223], v[100:103]
	v_mfma_f32_16x16x32_bf16 v[92:95], v[174:177], v[228:231], v[92:95]
	v_mfma_f32_16x16x32_bf16 v[84:87], v[204:207], v[228:231], v[84:87]
	v_mfma_f32_16x16x32_bf16 v[76:79], v[174:177], v[236:239], v[76:79]
	v_mfma_f32_16x16x32_bf16 v[68:71], v[204:207], v[236:239], v[68:71]
	v_mfma_f32_16x16x32_bf16 v[124:127], v[178:181], v[216:219], v[124:127]
	v_mfma_f32_16x16x32_bf16 v[116:119], v[208:211], v[216:219], v[116:119]
	v_mfma_f32_16x16x32_bf16 v[108:111], v[178:181], v[224:227], v[108:111]
	v_mfma_f32_16x16x32_bf16 v[100:103], v[208:211], v[224:227], v[100:103]
	v_mfma_f32_16x16x32_bf16 v[92:95], v[178:181], v[232:235], v[92:95]
	v_mfma_f32_16x16x32_bf16 v[84:87], v[208:211], v[232:235], v[84:87]
	v_mfma_f32_16x16x32_bf16 v[76:79], v[178:181], v[240:243], v[76:79]
	v_mfma_f32_16x16x32_bf16 v[68:71], v[208:211], v[240:243], v[68:71]
	s_setprio 3
	s_barrier
	s_add_i32 s40, s61, s42
	s_add_i32 m0, s40, 0xffffff80
	ds_read_b128 v[212:215], v153 offset:49152
	ds_read_b128 v[216:219], v153 offset:50176
	ds_read_b128 v[220:223], v153 offset:51200
	ds_read_b128 v[224:227], v153 offset:52224
	ds_read_b128 v[228:231], v153 offset:53248
	ds_read_b128 v[232:235], v153 offset:54272
	ds_read_b128 v[236:239], v153 offset:55296
	ds_read_b128 v[240:243], v153 offset:56320
	global_load_lds_dwordx4 v2, s[38:39] offset:128
	s_add_i32 m0, s40, 0x1f80
	s_add_i32 s40, s62, s42
	global_load_lds_dwordx4 v132, s[38:39] offset:128
	s_add_u32 s38, s38, 0x80080
	s_addc_u32 s39, s39, 0
	s_mov_b32 m0, s40
	s_nop 0
	global_load_lds_dwordx4 v2, s[38:39]
	s_add_i32 m0, s40, 0x2000
	s_nop 0
	global_load_lds_dwordx4 v132, s[38:39]
	s_mov_b32 m0, s51
	s_nop 0
	global_load_lds_dwordx4 v136, s[100:101]
	s_mov_b32 m0, s53
	s_nop 0
	global_load_lds_dwordx4 v134, s[100:101]
	s_waitcnt vmcnt(8) lgkmcnt(0)
	s_barrier
	s_setprio 0
	s_waitcnt lgkmcnt(0)
	v_mfma_f32_16x16x32_bf16 v[64:67], v[142:145], v[212:215], v[64:67]
	v_mfma_f32_16x16x32_bf16 v[56:59], v[154:157], v[212:215], v[56:59]
	v_mfma_f32_16x16x32_bf16 v[48:51], v[142:145], v[220:223], v[48:51]
	v_mfma_f32_16x16x32_bf16 v[40:43], v[154:157], v[220:223], v[40:43]
	v_mfma_f32_16x16x32_bf16 v[32:35], v[142:145], v[228:231], v[32:35]
	v_mfma_f32_16x16x32_bf16 v[24:27], v[154:157], v[228:231], v[24:27]
	v_mfma_f32_16x16x32_bf16 v[16:19], v[142:145], v[236:239], v[16:19]
	v_mfma_f32_16x16x32_bf16 v[8:11], v[154:157], v[236:239], v[8:11]
	v_mfma_f32_16x16x32_bf16 v[64:67], v[146:149], v[216:219], v[64:67]
	v_mfma_f32_16x16x32_bf16 v[56:59], v[158:161], v[216:219], v[56:59]
	v_mfma_f32_16x16x32_bf16 v[48:51], v[146:149], v[224:227], v[48:51]
	v_mfma_f32_16x16x32_bf16 v[40:43], v[158:161], v[224:227], v[40:43]
	v_mfma_f32_16x16x32_bf16 v[32:35], v[146:149], v[232:235], v[32:35]
	v_mfma_f32_16x16x32_bf16 v[24:27], v[158:161], v[232:235], v[24:27]
	v_mfma_f32_16x16x32_bf16 v[16:19], v[146:149], v[240:243], v[16:19]
	v_mfma_f32_16x16x32_bf16 v[8:11], v[158:161], v[240:243], v[8:11]
	v_mfma_f32_16x16x32_bf16 v[60:63], v[174:177], v[212:215], v[60:63]
	ds_read_b128 v[142:145], v249
	v_mfma_f32_16x16x32_bf16 v[52:55], v[204:207], v[212:215], v[52:55]
	ds_read_b128 v[146:149], v249 offset:1024
	v_mfma_f32_16x16x32_bf16 v[44:47], v[174:177], v[220:223], v[44:47]
	ds_read_b128 v[154:157], v249 offset:2048
	v_mfma_f32_16x16x32_bf16 v[36:39], v[204:207], v[220:223], v[36:39]
	ds_read_b128 v[158:161], v249 offset:3072
	v_mfma_f32_16x16x32_bf16 v[28:31], v[174:177], v[228:231], v[28:31]
	v_mfma_f32_16x16x32_bf16 v[20:23], v[204:207], v[228:231], v[20:23]
	v_mfma_f32_16x16x32_bf16 v[12:15], v[174:177], v[236:239], v[12:15]
	v_mfma_f32_16x16x32_bf16 v[4:7], v[204:207], v[236:239], v[4:7]
	v_mfma_f32_16x16x32_bf16 v[60:63], v[178:181], v[216:219], v[60:63]
	v_mfma_f32_16x16x32_bf16 v[52:55], v[208:211], v[216:219], v[52:55]
	v_mfma_f32_16x16x32_bf16 v[44:47], v[178:181], v[224:227], v[44:47]
	v_mfma_f32_16x16x32_bf16 v[36:39], v[208:211], v[224:227], v[36:39]
	v_mfma_f32_16x16x32_bf16 v[28:31], v[178:181], v[232:235], v[28:31]
	v_mfma_f32_16x16x32_bf16 v[20:23], v[208:211], v[232:235], v[20:23]
	v_mfma_f32_16x16x32_bf16 v[12:15], v[178:181], v[240:243], v[12:15]
	v_mfma_f32_16x16x32_bf16 v[4:7], v[208:211], v[240:243], v[4:7]
	s_setprio 3
	s_barrier
	s_add_i32 s60, s60, 2
	s_add_u32 s36, s36, 0x100
	s_addc_u32 s37, s37, 0
	s_add_u32 s58, s58, 0x100
	s_addc_u32 s59, s59, 0
	s_cmp_gt_u32 s60, 29
	s_cbranch_scc0 .LBB0_301
	s_and_b64 vcc, exec, s[8:9]
	s_cbranch_vccz .LBB0_304
	s_barrier

; #define PG8_STAGE(bufoff, gbase, voff) do { _Pragma("unroll") for (int _i = 0; _i < 2; ++_i) \
;         __builtin_amdgcn_global_load_lds((const unsigned*)((const char*)(gbase) + (voff)[_i]), (PG8_LAS unsigned*)(lds + (bufoff) + ldsw + _i * 8192), 16, 0, 0); } while (0)
; #define PG8_LDA(dst, b, h) do { _Pragma("unroll") for (int m = 0; m < 4; ++m) _Pragma("unroll") for (int k = 0; k < 2; ++k) dst[m][k] = *(const PG8_LAS bf16x8*)(lds + PG8_SA(b, h) + aoff + m * 2048 + k * 1024); } while (0)
; #define PG8_LDB(dst, b, h) do { _Pragma("unroll") for (int n = 0; n < 2; ++n) _Pragma("unroll") for (int k = 0; k < 2; ++k) dst[n][k] = *(const PG8_LAS bf16x8*)(lds + PG8_SB(b, h) + boff + n * 2048 + k * 1024); } while (0)
; #define PG8_MMA(ai, bj, At, Bt) do { __builtin_amdgcn_s_setprio(1); _Pragma("unroll") for (int m = 0; m < 4; ++m) _Pragma("unroll") for (int n = 0; n < 2; ++n) _Pragma("unroll") for (int k = 0; k < 2; ++k) \
;         acc[ai][bj][m][n] = __builtin_amdgcn_mfma_f32_16x16x32_bf16(Bt[n][k], At[m][k], acc[ai][bj][m][n], 0, 0, 0); __builtin_amdgcn_s_setprio(0); } while (0)
; #define PG8_WAIT_V(n) asm volatile("s_waitcnt vmcnt(" #n ")" ::: "memory")
; template <class Epi, class Sched, bool ALIGN_EPI = false, bool SP2 = false>
; __device__ __forceinline__ void gemm_phase(PG8_LAS unsigned char* lds, const Gemm g, const Sched& S, const Epi& E) {
;     ...
;         for (int t = 0; t < nt; t += 2) {
;             const bool last = (t == nt - 2);
;             const char* a1 = cA + (size_t)(t + 1) * kstep;
;             const char* a2 = last ? nA : cA + (size_t)(t + 2) * kstep; const char* b2 = last ? nB : cB + (size_t)(t + 2) * kstep;
;             const char* a3 = a2 + kstep; const char* b3 = b2 + kstep;
;             if (last && has_next) S.a_ready(nxt);
;             if constexpr (SP2) {
;             PG8_LDB(B0, 0, 0); PG8_LDB(B1, 0, 1); PG8_SCHED; PG8_LDA(At, 0, 0); PG8_STAGE(PG8_SA(1, 1), a1 + hstep, voffA);
;             PG8_WAIT_V(8); PG8_WAIT_L(0); PG8_BAR; PG8_MMA(0, 0, At, B0); PG8_MMA(0, 1, At, B1); PG8_BAR; PG8_SCHED;
;     ...
;         if (zero_acc) {
; #pragma unroll
;         for (int a = 0; a < 2; ++a)
; #pragma unroll
;             for (int b = 0; b < 2; ++b)
; #pragma unroll
;                 for (int m = 0; m < 4; ++m)
; #pragma unroll
;                     for (int n = 0; n < 2; ++n) acc[a][b][m][n] = (f32x4){0.f, 0.f, 0.f, 0.f};
.LBB0_574:
	s_add_u32 s61, s36, 0x100
	v_mov_b32_e32 v4, 0
	s_addc_u32 s62, s37, 0
	s_mov_b32 s63, -2
	s_waitcnt lgkmcnt(0)
	v_mov_b32_e32 v5, v4
	v_mov_b32_e32 v6, v4
	v_mov_b32_e32 v7, v4
	v_mov_b32_e32 v8, v4
	v_mov_b32_e32 v9, v4
	v_mov_b32_e32 v10, v4
	v_mov_b32_e32 v11, v4
	v_mov_b32_e32 v20, v4
	v_mov_b32_e32 v21, v4
	s_waitcnt vmcnt(0)
	v_mov_b32_e32 v22, v4
	v_mov_b32_e32 v23, v4
	v_mov_b32_e32 v24, v4
	v_mov_b32_e32 v25, v4
	v_mov_b32_e32 v26, v4
	v_mov_b32_e32 v27, v4
	v_mov_b32_e32 v36, v4
	v_mov_b32_e32 v37, v4
	v_mov_b32_e32 v38, v4
	v_mov_b32_e32 v39, v4
	v_mov_b32_e32 v40, v4
	v_mov_b32_e32 v41, v4
	v_mov_b32_e32 v42, v4
	v_mov_b32_e32 v43, v4
	v_mov_b32_e32 v52, v4
	v_mov_b32_e32 v53, v4
	v_mov_b32_e32 v54, v4
	v_mov_b32_e32 v55, v4
	v_mov_b32_e32 v56, v4
	v_mov_b32_e32 v57, v4
	v_mov_b32_e32 v58, v4
	v_mov_b32_e32 v59, v4
	v_mov_b32_e32 v12, v4
	v_mov_b32_e32 v13, v4
	v_mov_b32_e32 v14, v4
	v_mov_b32_e32 v15, v4
	v_mov_b32_e32 v16, v4
	v_mov_b32_e32 v17, v4
	v_mov_b32_e32 v18, v4
	v_mov_b32_e32 v19, v4
	v_mov_b32_e32 v28, v4
	v_mov_b32_e32 v29, v4
	v_mov_b32_e32 v30, v4
	v_mov_b32_e32 v31, v4
	v_mov_b32_e32 v32, v4
	v_mov_b32_e32 v33, v4
	v_mov_b32_e32 v34, v4
	v_mov_b32_e32 v35, v4
	v_mov_b32_e32 v44, v4
	v_mov_b32_e32 v45, v4
	v_mov_b32_e32 v46, v4
	v_mov_b32_e32 v47, v4
	v_mov_b32_e32 v48, v4
	v_mov_b32_e32 v49, v4
	v_mov_b32_e32 v50, v4
	v_mov_b32_e32 v51, v4
	v_mov_b32_e32 v60, v4
	v_mov_b32_e32 v61, v4
	v_mov_b32_e32 v62, v4
	v_mov_b32_e32 v63, v4
	v_mov_b32_e32 v64, v4
	v_mov_b32_e32 v65, v4
	v_mov_b32_e32 v66, v4
	v_mov_b32_e32 v67, v4
	v_mov_b32_e32 v68, v4
	v_mov_b32_e32 v69, v4
	v_mov_b32_e32 v70, v4
	v_mov_b32_e32 v71, v4
	v_mov_b32_e32 v72, v4
	v_mov_b32_e32 v73, v4
	v_mov_b32_e32 v74, v4
	v_mov_b32_e32 v75, v4
	v_mov_b32_e32 v84, v4
	v_mov_b32_e32 v85, v4
	v_mov_b32_e32 v86, v4
	v_mov_b32_e32 v87, v4
	v_mov_b32_e32 v88, v4
	v_mov_b32_e32 v89, v4
	v_mov_b32_e32 v90, v4
	v_mov_b32_e32 v91, v4
	v_mov_b32_e32 v100, v4
	v_mov_b32_e32 v101, v4
	v_mov_b32_e32 v102, v4
	v_mov_b32_e32 v103, v4
	v_mov_b32_e32 v104, v4
	v_mov_b32_e32 v105, v4
	v_mov_b32_e32 v106, v4
	v_mov_b32_e32 v107, v4
	v_mov_b32_e32 v116, v4
	v_mov_b32_e32 v117, v4
	v_mov_b32_e32 v118, v4
	v_mov_b32_e32 v119, v4
	v_mov_b32_e32 v120, v4
	v_mov_b32_e32 v121, v4
	v_mov_b32_e32 v122, v4
	v_mov_b32_e32 v123, v4
	v_mov_b32_e32 v76, v4
	v_mov_b32_e32 v77, v4
	v_mov_b32_e32 v78, v4
	v_mov_b32_e32 v79, v4
	v_mov_b32_e32 v80, v4
	v_mov_b32_e32 v81, v4
	v_mov_b32_e32 v82, v4
	v_mov_b32_e32 v83, v4
	v_mov_b32_e32 v92, v4
	v_mov_b32_e32 v93, v4
	v_mov_b32_e32 v94, v4
	v_mov_b32_e32 v95, v4
	v_mov_b32_e32 v96, v4
	v_mov_b32_e32 v97, v4
	v_mov_b32_e32 v98, v4
	v_mov_b32_e32 v99, v4
	v_mov_b32_e32 v108, v4
	v_mov_b32_e32 v109, v4
	v_mov_b32_e32 v110, v4
	v_mov_b32_e32 v111, v4
	v_mov_b32_e32 v112, v4
	v_mov_b32_e32 v113, v4
	v_mov_b32_e32 v114, v4
	v_mov_b32_e32 v115, v4
	v_mov_b32_e32 v124, v4
	v_mov_b32_e32 v125, v4
	v_mov_b32_e32 v126, v4
	v_mov_b32_e32 v127, v4
	v_mov_b32_e32 v128, v4
	v_mov_b32_e32 v129, v4
	v_mov_b32_e32 v130, v4
	v_mov_b32_e32 v131, v4
	v_add_u32_e32 v247, 0x10000, v173
	ds_read_b128 v[142:145], v247
	ds_read_b128 v[146:149], v247 offset:1024
	ds_read_b128 v[150:153], v247 offset:2048
	ds_read_b128 v[154:157], v247 offset:3072
	.p2align 6
	s_nop 0
.LBB0_575:
	s_add_u32 s36, s34, 0x100
	s_addc_u32 s37, s35, 0
	s_add_i32 s64, 0, 0x10000
	s_cmpk_eq_i32 s63, 0x52
	s_cselect_b32 s41, s5, s37
	s_cselect_b32 s40, s4, s36
	s_cselect_b32 s39, s31, s62
	s_cselect_b32 s38, s30, s61
	s_add_i32 s65, 0, 0x14000
	ds_read_b128 v[158:161], v247 offset:16384
	ds_read_b128 v[174:177], v247 offset:17408
	ds_read_b128 v[180:183], v247 offset:18432
	ds_read_b128 v[204:207], v247 offset:19456
	v_lshl_add_u64 v[162:163], s[34:35], 0, v[138:139]
	s_add_i32 m0, s47, 0xc000
	ds_read_b128 v[208:211], v179
	ds_read_b128 v[212:215], v179 offset:1024
	ds_read_b128 v[216:219], v179 offset:2048
	ds_read_b128 v[220:223], v179 offset:3072
	ds_read_b128 v[224:227], v179 offset:4096
	ds_read_b128 v[228:231], v179 offset:5120
	ds_read_b128 v[232:235], v179 offset:6144
	ds_read_b128 v[236:239], v179 offset:7168
	global_load_lds_dwordx4 v[162:163], off
	v_lshl_add_u64 v[162:163], s[34:35], 0, v[140:141]
	s_add_i32 m0, s47, 0xe000
	s_nop 0
	global_load_lds_dwordx4 v[162:163], off
	s_nop 0
	s_waitcnt vmcnt(8) lgkmcnt(0)
	s_barrier
	s_setprio 0
	s_waitcnt lgkmcnt(0)
	v_mfma_f32_16x16x32_bf16 v[128:131], v[142:145], v[208:211], v[128:131]
	v_mfma_f32_16x16x32_bf16 v[124:127], v[150:153], v[208:211], v[124:127]
	v_mfma_f32_16x16x32_bf16 v[112:115], v[142:145], v[216:219], v[112:115]
	v_mfma_f32_16x16x32_bf16 v[108:111], v[150:153], v[216:219], v[108:111]
	v_mfma_f32_16x16x32_bf16 v[96:99], v[142:145], v[224:227], v[96:99]
	v_mfma_f32_16x16x32_bf16 v[92:95], v[150:153], v[224:227], v[92:95]
	v_mfma_f32_16x16x32_bf16 v[80:83], v[142:145], v[232:235], v[80:83]
	v_mfma_f32_16x16x32_bf16 v[76:79], v[150:153], v[232:235], v[76:79]
	v_mfma_f32_16x16x32_bf16 v[128:131], v[146:149], v[212:215], v[128:131]
	v_mfma_f32_16x16x32_bf16 v[124:127], v[154:157], v[212:215], v[124:127]
	v_mfma_f32_16x16x32_bf16 v[112:115], v[146:149], v[220:223], v[112:115]
	v_mfma_f32_16x16x32_bf16 v[108:111], v[154:157], v[220:223], v[108:111]
	v_mfma_f32_16x16x32_bf16 v[96:99], v[146:149], v[228:231], v[96:99]
	v_mfma_f32_16x16x32_bf16 v[92:95], v[154:157], v[228:231], v[92:95]
	v_mfma_f32_16x16x32_bf16 v[80:83], v[146:149], v[236:239], v[80:83]
	v_mfma_f32_16x16x32_bf16 v[76:79], v[154:157], v[236:239], v[76:79]
	v_mfma_f32_16x16x32_bf16 v[120:123], v[158:161], v[208:211], v[120:123]
	v_mfma_f32_16x16x32_bf16 v[116:119], v[180:183], v[208:211], v[116:119]
	v_mfma_f32_16x16x32_bf16 v[104:107], v[158:161], v[216:219], v[104:107]
	v_mfma_f32_16x16x32_bf16 v[100:103], v[180:183], v[216:219], v[100:103]
	v_mfma_f32_16x16x32_bf16 v[88:91], v[158:161], v[224:227], v[88:91]
	v_mfma_f32_16x16x32_bf16 v[84:87], v[180:183], v[224:227], v[84:87]
	v_mfma_f32_16x16x32_bf16 v[72:75], v[158:161], v[232:235], v[72:75]
	v_mfma_f32_16x16x32_bf16 v[68:71], v[180:183], v[232:235], v[68:71]
	v_mfma_f32_16x16x32_bf16 v[120:123], v[174:177], v[212:215], v[120:123]
	v_mfma_f32_16x16x32_bf16 v[116:119], v[204:207], v[212:215], v[116:119]
	v_mfma_f32_16x16x32_bf16 v[104:107], v[174:177], v[220:223], v[104:107]
	v_mfma_f32_16x16x32_bf16 v[100:103], v[204:207], v[220:223], v[100:103]
	v_mfma_f32_16x16x32_bf16 v[88:91], v[174:177], v[228:231], v[88:91]
	v_mfma_f32_16x16x32_bf16 v[84:87], v[204:207], v[228:231], v[84:87]
	v_mfma_f32_16x16x32_bf16 v[72:75], v[174:177], v[236:239], v[72:75]
	v_mfma_f32_16x16x32_bf16 v[68:71], v[204:207], v[236:239], v[68:71]
	s_setprio 3
	s_barrier
; #define PG8_STAGE(bufoff, gbase, voff) do { _Pragma("unroll") for (int _i = 0; _i < 2; ++_i) \
;         __builtin_amdgcn_global_load_lds((const unsigned*)((const char*)(gbase) + (voff)[_i]), (PG8_LAS unsigned*)(lds + (bufoff) + ldsw + _i * 8192), 16, 0, 0); } while (0)
; #define PG8_LDA(dst, b, h) do { _Pragma("unroll") for (int m = 0; m < 4; ++m) _Pragma("unroll") for (int k = 0; k < 2; ++k) dst[m][k] = *(const PG8_LAS bf16x8*)(lds + PG8_SA(b, h) + aoff + m * 2048 + k * 1024); } while (0)
; #define PG8_LDB(dst, b, h) do { _Pragma("unroll") for (int n = 0; n < 2; ++n) _Pragma("unroll") for (int k = 0; k < 2; ++k) dst[n][k] = *(const PG8_LAS bf16x8*)(lds + PG8_SB(b, h) + boff + n * 2048 + k * 1024); } while (0)
; #define PG8_MMA(ai, bj, At, Bt) do { __builtin_amdgcn_s_setprio(1); _Pragma("unroll") for (int m = 0; m < 4; ++m) _Pragma("unroll") for (int n = 0; n < 2; ++n) _Pragma("unroll") for (int k = 0; k < 2; ++k) \
;         acc[ai][bj][m][n] = __builtin_amdgcn_mfma_f32_16x16x32_bf16(Bt[n][k], At[m][k], acc[ai][bj][m][n], 0, 0, 0); __builtin_amdgcn_s_setprio(0); } while (0)
; #define PG8_WAIT_V(n) asm volatile("s_waitcnt vmcnt(" #n ")" ::: "memory")
; #define PG8_WAIT_L(n) asm volatile("s_waitcnt lgkmcnt(" #n ")" ::: "memory")
; #define PG8_BAR __builtin_amdgcn_s_barrier()
; #define PG8_SCHED __builtin_amdgcn_sched_barrier(0)
; template <class Epi, class Sched, bool ALIGN_EPI = false, bool SP2 = false>
; __device__ __forceinline__ void gemm_phase(PG8_LAS unsigned char* lds, const Gemm g, const Sched& S, const Epi& E) {
;     ...
;             PG8_LDA(At, 0, 1); PG8_STAGE(PG8_SB(0, 0), b2, voffB); PG8_STAGE(PG8_SB(0, 1), b2 + hstep, voffB); PG8_STAGE(PG8_SA(0, 0), a2, voffA);
;             PG8_WAIT_V(8); PG8_WAIT_L(0); PG8_BAR; PG8_MMA(1, 0, At, B0); PG8_MMA(1, 1, At, B1); PG8_BAR; PG8_SCHED;
;             PG8_LDB(B0, 1, 0); PG8_LDB(B1, 1, 1); PG8_SCHED; PG8_LDA(At, 1, 0); PG8_STAGE(PG8_SA(0, 1), a2 + hstep, voffA);
	s_add_i32 s34, s64, s46
	s_mov_b32 m0, s34
	ds_read_b128 v[208:211], v179 offset:16384
	ds_read_b128 v[212:215], v179 offset:17408
	ds_read_b128 v[216:219], v179 offset:18432
	ds_read_b128 v[220:223], v179 offset:19456
	ds_read_b128 v[224:227], v179 offset:20480
	ds_read_b128 v[228:231], v179 offset:21504
	ds_read_b128 v[232:235], v179 offset:22528
	ds_read_b128 v[236:239], v179 offset:23552
	global_load_lds_dwordx4 v2, s[38:39]
	s_add_i32 m0, s34, 0x2000
	s_add_u32 s34, s38, 0x158000
	s_addc_u32 s35, s39, 0
	s_add_i32 s64, s65, s46
	global_load_lds_dwordx4 v132, s[38:39]
	s_mov_b32 m0, s64
	s_nop 0
	global_load_lds_dwordx4 v2, s[34:35]
	s_add_i32 m0, s64, 0x2000
	s_nop 0
	global_load_lds_dwordx4 v132, s[34:35]
	s_mov_b32 m0, s47
	s_nop 0
	global_load_lds_dwordx4 v2, s[40:41]
	s_mov_b32 m0, s48
	s_nop 0
	global_load_lds_dwordx4 v132, s[40:41]
	s_nop 0
	s_waitcnt vmcnt(8) lgkmcnt(0)
	s_barrier
	s_setprio 0
	s_waitcnt lgkmcnt(0)
	v_mfma_f32_16x16x32_bf16 v[64:67], v[142:145], v[208:211], v[64:67]
	v_mfma_f32_16x16x32_bf16 v[60:63], v[150:153], v[208:211], v[60:63]
	v_mfma_f32_16x16x32_bf16 v[48:51], v[142:145], v[216:219], v[48:51]
	v_mfma_f32_16x16x32_bf16 v[44:47], v[150:153], v[216:219], v[44:47]
	v_mfma_f32_16x16x32_bf16 v[32:35], v[142:145], v[224:227], v[32:35]
	v_mfma_f32_16x16x32_bf16 v[28:31], v[150:153], v[224:227], v[28:31]
	v_mfma_f32_16x16x32_bf16 v[16:19], v[142:145], v[232:235], v[16:19]
	v_mfma_f32_16x16x32_bf16 v[12:15], v[150:153], v[232:235], v[12:15]
	v_mfma_f32_16x16x32_bf16 v[64:67], v[146:149], v[212:215], v[64:67]
	v_mfma_f32_16x16x32_bf16 v[60:63], v[154:157], v[212:215], v[60:63]
	v_mfma_f32_16x16x32_bf16 v[48:51], v[146:149], v[220:223], v[48:51]
	v_mfma_f32_16x16x32_bf16 v[44:47], v[154:157], v[220:223], v[44:47]
	v_mfma_f32_16x16x32_bf16 v[32:35], v[146:149], v[228:231], v[32:35]
	v_mfma_f32_16x16x32_bf16 v[28:31], v[154:157], v[228:231], v[28:31]
	v_mfma_f32_16x16x32_bf16 v[16:19], v[146:149], v[236:239], v[16:19]
	v_mfma_f32_16x16x32_bf16 v[12:15], v[154:157], v[236:239], v[12:15]
	v_mfma_f32_16x16x32_bf16 v[56:59], v[158:161], v[208:211], v[56:59]
	ds_read_b128 v[142:145], v247 offset:32768
	v_mfma_f32_16x16x32_bf16 v[52:55], v[180:183], v[208:211], v[52:55]
	ds_read_b128 v[146:149], v247 offset:33792
	v_mfma_f32_16x16x32_bf16 v[40:43], v[158:161], v[216:219], v[40:43]
	ds_read_b128 v[150:153], v247 offset:34816
	v_mfma_f32_16x16x32_bf16 v[36:39], v[180:183], v[216:219], v[36:39]
	ds_read_b128 v[154:157], v247 offset:35840
	v_mfma_f32_16x16x32_bf16 v[24:27], v[158:161], v[224:227], v[24:27]
	v_mfma_f32_16x16x32_bf16 v[20:23], v[180:183], v[224:227], v[20:23]
	v_mfma_f32_16x16x32_bf16 v[8:11], v[158:161], v[232:235], v[8:11]
	v_mfma_f32_16x16x32_bf16 v[4:7], v[180:183], v[232:235], v[4:7]
	v_mfma_f32_16x16x32_bf16 v[56:59], v[174:177], v[212:215], v[56:59]
	v_mfma_f32_16x16x32_bf16 v[52:55], v[204:207], v[212:215], v[52:55]
	v_mfma_f32_16x16x32_bf16 v[40:43], v[174:177], v[220:223], v[40:43]
	v_mfma_f32_16x16x32_bf16 v[36:39], v[204:207], v[220:223], v[36:39]
	v_mfma_f32_16x16x32_bf16 v[24:27], v[174:177], v[228:231], v[24:27]
	v_mfma_f32_16x16x32_bf16 v[20:23], v[204:207], v[228:231], v[20:23]
	v_mfma_f32_16x16x32_bf16 v[8:11], v[174:177], v[236:239], v[8:11]
	v_mfma_f32_16x16x32_bf16 v[4:7], v[204:207], v[236:239], v[4:7]
	s_setprio 3
	s_barrier
	s_add_i32 s64, 0, 0x18000
	s_add_i32 s65, 0, 0x1c000
	ds_read_b128 v[158:161], v247 offset:49152
	ds_read_b128 v[174:177], v247 offset:50176
	ds_read_b128 v[180:183], v247 offset:51200
	ds_read_b128 v[204:207], v247 offset:52224
	s_add_u32 s34, s40, 0x158000
	s_addc_u32 s35, s41, 0
	s_mov_b32 m0, s49
	ds_read_b128 v[208:211], v179 offset:32768
	ds_read_b128 v[212:215], v179 offset:33792
	ds_read_b128 v[216:219], v179 offset:34816
	ds_read_b128 v[220:223], v179 offset:35840
	ds_read_b128 v[224:227], v179 offset:36864
	ds_read_b128 v[228:231], v179 offset:37888
	ds_read_b128 v[232:235], v179 offset:38912
	ds_read_b128 v[236:239], v179 offset:39936
	global_load_lds_dwordx4 v2, s[34:35]
	s_mov_b32 m0, s50
	s_nop 0
	global_load_lds_dwordx4 v132, s[34:35]
	s_waitcnt vmcnt(8) lgkmcnt(0)
	s_barrier
; #define PG8_STAGE(bufoff, gbase, voff) do { _Pragma("unroll") for (int _i = 0; _i < 2; ++_i) \
;         __builtin_amdgcn_global_load_lds((const unsigned*)((const char*)(gbase) + (voff)[_i]), (PG8_LAS unsigned*)(lds + (bufoff) + ldsw + _i * 8192), 16, 0, 0); } while (0)
; #define PG8_LDA(dst, b, h) do { _Pragma("unroll") for (int m = 0; m < 4; ++m) _Pragma("unroll") for (int k = 0; k < 2; ++k) dst[m][k] = *(const PG8_LAS bf16x8*)(lds + PG8_SA(b, h) + aoff + m * 2048 + k * 1024); } while (0)
; #define PG8_MMA(ai, bj, At, Bt) do { __builtin_amdgcn_s_setprio(1); _Pragma("unroll") for (int m = 0; m < 4; ++m) _Pragma("unroll") for (int n = 0; n < 2; ++n) _Pragma("unroll") for (int k = 0; k < 2; ++k) \
;         acc[ai][bj][m][n] = __builtin_amdgcn_mfma_f32_16x16x32_bf16(Bt[n][k], At[m][k], acc[ai][bj][m][n], 0, 0, 0); __builtin_amdgcn_s_setprio(0); } while (0)
; #define PG8_WAIT_V(n) asm volatile("s_waitcnt vmcnt(" #n ")" ::: "memory")
; #define PG8_WAIT_L(n) asm volatile("s_waitcnt lgkmcnt(" #n ")" ::: "memory")
; #define PG8_BAR __builtin_amdgcn_s_barrier()
; #define PG8_SCHED __builtin_amdgcn_sched_barrier(0)
; template <class Epi, class Sched, bool ALIGN_EPI = false, bool SP2 = false>
; __device__ __forceinline__ void gemm_phase(PG8_LAS unsigned char* lds, const Gemm g, const Sched& S, const Epi& E) {
;     ...
;             PG8_WAIT_V(8); PG8_WAIT_L(0); PG8_BAR; PG8_MMA(0, 0, At, B0); PG8_MMA(0, 1, At, B1); PG8_BAR; PG8_SCHED;
;             PG8_LDA(At, 1, 1); PG8_STAGE(PG8_SB(1, 0), b3, voffB); PG8_STAGE(PG8_SB(1, 1), b3 + hstep, voffB); PG8_STAGE(PG8_SA(1, 0), a3, voffA);
;             PG8_WAIT_V(8); PG8_WAIT_L(0); PG8_BAR; PG8_MMA(1, 0, At, B0); PG8_MMA(1, 1, At, B1); PG8_BAR; PG8_SCHED;
	s_setprio 0
	s_waitcnt lgkmcnt(0)
	v_mfma_f32_16x16x32_bf16 v[128:131], v[142:145], v[208:211], v[128:131]
	v_mfma_f32_16x16x32_bf16 v[124:127], v[150:153], v[208:211], v[124:127]
	v_mfma_f32_16x16x32_bf16 v[112:115], v[142:145], v[216:219], v[112:115]
	v_mfma_f32_16x16x32_bf16 v[108:111], v[150:153], v[216:219], v[108:111]
	v_mfma_f32_16x16x32_bf16 v[96:99], v[142:145], v[224:227], v[96:99]
	v_mfma_f32_16x16x32_bf16 v[92:95], v[150:153], v[224:227], v[92:95]
	v_mfma_f32_16x16x32_bf16 v[80:83], v[142:145], v[232:235], v[80:83]
	v_mfma_f32_16x16x32_bf16 v[76:79], v[150:153], v[232:235], v[76:79]
	v_mfma_f32_16x16x32_bf16 v[128:131], v[146:149], v[212:215], v[128:131]
	v_mfma_f32_16x16x32_bf16 v[124:127], v[154:157], v[212:215], v[124:127]
	v_mfma_f32_16x16x32_bf16 v[112:115], v[146:149], v[220:223], v[112:115]
	v_mfma_f32_16x16x32_bf16 v[108:111], v[154:157], v[220:223], v[108:111]
	v_mfma_f32_16x16x32_bf16 v[96:99], v[146:149], v[228:231], v[96:99]
	v_mfma_f32_16x16x32_bf16 v[92:95], v[154:157], v[228:231], v[92:95]
	v_mfma_f32_16x16x32_bf16 v[80:83], v[146:149], v[236:239], v[80:83]
	v_mfma_f32_16x16x32_bf16 v[76:79], v[154:157], v[236:239], v[76:79]
	v_mfma_f32_16x16x32_bf16 v[120:123], v[158:161], v[208:211], v[120:123]
	v_mfma_f32_16x16x32_bf16 v[116:119], v[180:183], v[208:211], v[116:119]
	v_mfma_f32_16x16x32_bf16 v[104:107], v[158:161], v[216:219], v[104:107]
	v_mfma_f32_16x16x32_bf16 v[100:103], v[180:183], v[216:219], v[100:103]
	v_mfma_f32_16x16x32_bf16 v[88:91], v[158:161], v[224:227], v[88:91]
	v_mfma_f32_16x16x32_bf16 v[84:87], v[180:183], v[224:227], v[84:87]
	v_mfma_f32_16x16x32_bf16 v[72:75], v[158:161], v[232:235], v[72:75]
	v_mfma_f32_16x16x32_bf16 v[68:71], v[180:183], v[232:235], v[68:71]
	v_mfma_f32_16x16x32_bf16 v[120:123], v[174:177], v[212:215], v[120:123]
	v_mfma_f32_16x16x32_bf16 v[116:119], v[204:207], v[212:215], v[116:119]
	v_mfma_f32_16x16x32_bf16 v[104:107], v[174:177], v[220:223], v[104:107]
	v_mfma_f32_16x16x32_bf16 v[100:103], v[204:207], v[220:223], v[100:103]
	v_mfma_f32_16x16x32_bf16 v[88:91], v[174:177], v[228:231], v[88:91]
	v_mfma_f32_16x16x32_bf16 v[84:87], v[204:207], v[228:231], v[84:87]
	v_mfma_f32_16x16x32_bf16 v[72:75], v[174:177], v[236:239], v[72:75]
	v_mfma_f32_16x16x32_bf16 v[68:71], v[204:207], v[236:239], v[68:71]
	s_setprio 3
	s_barrier
	s_add_i32 s34, s64, s46
	s_add_i32 m0, s34, 0xffffff80
	ds_read_b128 v[208:211], v179 offset:49152
	ds_read_b128 v[212:215], v179 offset:50176
	ds_read_b128 v[216:219], v179 offset:51200
	ds_read_b128 v[220:223], v179 offset:52224
	ds_read_b128 v[224:227], v179 offset:53248
	ds_read_b128 v[228:231], v179 offset:54272
	ds_read_b128 v[232:235], v179 offset:55296
	ds_read_b128 v[236:239], v179 offset:56320
	global_load_lds_dwordx4 v2, s[38:39] offset:128
	s_add_i32 m0, s34, 0x1f80
	s_add_u32 s34, s38, 0x158080
	s_addc_u32 s35, s39, 0
	global_load_lds_dwordx4 v132, s[38:39] offset:128
	s_add_i32 s38, s65, s46
	s_mov_b32 m0, s38
	s_nop 0
	global_load_lds_dwordx4 v2, s[34:35]
	s_add_i32 m0, s38, 0x2000
	s_nop 0
	global_load_lds_dwordx4 v132, s[34:35]
	s_add_i32 m0, s53, 0xffffff80
	s_nop 0
	global_load_lds_dwordx4 v2, s[40:41] offset:128
	s_add_i32 m0, s54, 0xffffff80
	s_nop 0
	global_load_lds_dwordx4 v132, s[40:41] offset:128
	s_waitcnt vmcnt(8) lgkmcnt(0)
	s_barrier
	s_setprio 0
	s_waitcnt lgkmcnt(0)
	v_mfma_f32_16x16x32_bf16 v[64:67], v[142:145], v[208:211], v[64:67]
	v_mfma_f32_16x16x32_bf16 v[60:63], v[150:153], v[208:211], v[60:63]
	v_mfma_f32_16x16x32_bf16 v[48:51], v[142:145], v[216:219], v[48:51]
	v_mfma_f32_16x16x32_bf16 v[44:47], v[150:153], v[216:219], v[44:47]
	v_mfma_f32_16x16x32_bf16 v[32:35], v[142:145], v[224:227], v[32:35]
	v_mfma_f32_16x16x32_bf16 v[28:31], v[150:153], v[224:227], v[28:31]
	v_mfma_f32_16x16x32_bf16 v[16:19], v[142:145], v[232:235], v[16:19]
	v_mfma_f32_16x16x32_bf16 v[12:15], v[150:153], v[232:235], v[12:15]
	v_mfma_f32_16x16x32_bf16 v[64:67], v[146:149], v[212:215], v[64:67]
	v_mfma_f32_16x16x32_bf16 v[60:63], v[154:157], v[212:215], v[60:63]
	v_mfma_f32_16x16x32_bf16 v[48:51], v[146:149], v[220:223], v[48:51]
	v_mfma_f32_16x16x32_bf16 v[44:47], v[154:157], v[220:223], v[44:47]
	v_mfma_f32_16x16x32_bf16 v[32:35], v[146:149], v[228:231], v[32:35]
	v_mfma_f32_16x16x32_bf16 v[28:31], v[154:157], v[228:231], v[28:31]
	v_mfma_f32_16x16x32_bf16 v[16:19], v[146:149], v[236:239], v[16:19]
	v_mfma_f32_16x16x32_bf16 v[12:15], v[154:157], v[236:239], v[12:15]
	v_mfma_f32_16x16x32_bf16 v[56:59], v[158:161], v[208:211], v[56:59]
	ds_read_b128 v[142:145], v247
	v_mfma_f32_16x16x32_bf16 v[52:55], v[180:183], v[208:211], v[52:55]
	ds_read_b128 v[146:149], v247 offset:1024
	v_mfma_f32_16x16x32_bf16 v[40:43], v[158:161], v[216:219], v[40:43]
	ds_read_b128 v[150:153], v247 offset:2048
	v_mfma_f32_16x16x32_bf16 v[36:39], v[180:183], v[216:219], v[36:39]
	ds_read_b128 v[154:157], v247 offset:3072
	v_mfma_f32_16x16x32_bf16 v[24:27], v[158:161], v[224:227], v[24:27]
	v_mfma_f32_16x16x32_bf16 v[20:23], v[180:183], v[224:227], v[20:23]
	v_mfma_f32_16x16x32_bf16 v[8:11], v[158:161], v[232:235], v[8:11]
	v_mfma_f32_16x16x32_bf16 v[4:7], v[180:183], v[232:235], v[4:7]
	v_mfma_f32_16x16x32_bf16 v[56:59], v[174:177], v[212:215], v[56:59]
	v_mfma_f32_16x16x32_bf16 v[52:55], v[204:207], v[212:215], v[52:55]
	v_mfma_f32_16x16x32_bf16 v[40:43], v[174:177], v[220:223], v[40:43]
	v_mfma_f32_16x16x32_bf16 v[36:39], v[204:207], v[220:223], v[36:39]
	v_mfma_f32_16x16x32_bf16 v[24:27], v[174:177], v[228:231], v[24:27]
	v_mfma_f32_16x16x32_bf16 v[20:23], v[204:207], v[228:231], v[20:23]
	v_mfma_f32_16x16x32_bf16 v[8:11], v[174:177], v[236:239], v[8:11]
	v_mfma_f32_16x16x32_bf16 v[4:7], v[204:207], v[236:239], v[4:7]
	s_setprio 3
	s_barrier
	s_add_i32 s63, s63, 2
	s_add_u32 s61, s61, 0x100
	s_addc_u32 s62, s62, 0
	s_cmpk_gt_u32 s63, 0x53
	s_mov_b64 s[34:35], s[36:37]
	s_cbranch_scc0 .LBB0_575
	s_and_b64 vcc, exec, s[28:29]
	s_cbranch_vccz .LBB0_578
	s_barrier

; #define PG8_STAGE(bufoff, gbase, voff) do { _Pragma("unroll") for (int _i = 0; _i < 2; ++_i) \
;         __builtin_amdgcn_global_load_lds((const unsigned*)((const char*)(gbase) + (voff)[_i]), (PG8_LAS unsigned*)(lds + (bufoff) + ldsw + _i * 8192), 16, 0, 0); } while (0)
; #define PG8_LDA(dst, b, h) do { _Pragma("unroll") for (int m = 0; m < 4; ++m) _Pragma("unroll") for (int k = 0; k < 2; ++k) dst[m][k] = *(const PG8_LAS bf16x8*)(lds + PG8_SA(b, h) + aoff + m * 2048 + k * 1024); } while (0)
; #define PG8_LDB(dst, b, h) do { _Pragma("unroll") for (int n = 0; n < 2; ++n) _Pragma("unroll") for (int k = 0; k < 2; ++k) dst[n][k] = *(const PG8_LAS bf16x8*)(lds + PG8_SB(b, h) + boff + n * 2048 + k * 1024); } while (0)
; #define PG8_MMA(ai, bj, At, Bt) do { __builtin_amdgcn_s_setprio(1); _Pragma("unroll") for (int m = 0; m < 4; ++m) _Pragma("unroll") for (int n = 0; n < 2; ++n) _Pragma("unroll") for (int k = 0; k < 2; ++k) \
;         acc[ai][bj][m][n] = __builtin_amdgcn_mfma_f32_16x16x32_bf16(Bt[n][k], At[m][k], acc[ai][bj][m][n], 0, 0, 0); __builtin_amdgcn_s_setprio(0); } while (0)
; #define PG8_WAIT_V(n) asm volatile("s_waitcnt vmcnt(" #n ")" ::: "memory")
; template <class Epi, class Sched, bool ALIGN_EPI = false, bool SP2 = false>
; __device__ __forceinline__ void gemm_phase(PG8_LAS unsigned char* lds, const Gemm g, const Sched& S, const Epi& E) {
;     ...
;         for (int t = 0; t < nt; t += 2) {
;             const bool last = (t == nt - 2);
;             const char* a1 = cA + (size_t)(t + 1) * kstep;
;             const char* a2 = last ? nA : cA + (size_t)(t + 2) * kstep; const char* b2 = last ? nB : cB + (size_t)(t + 2) * kstep;
;             const char* a3 = a2 + kstep; const char* b3 = b2 + kstep;
;             if (last && has_next) S.a_ready(nxt);
;             if constexpr (SP2) {
;             PG8_LDB(B0, 0, 0); PG8_LDB(B1, 0, 1); PG8_SCHED; PG8_LDA(At, 0, 0); PG8_STAGE(PG8_SA(1, 1), a1 + hstep, voffA);
;             PG8_WAIT_V(8); PG8_WAIT_L(0); PG8_BAR; PG8_MMA(0, 0, At, B0); PG8_MMA(0, 1, At, B1); PG8_BAR; PG8_SCHED;
;     ...
;         if (zero_acc) {
; #pragma unroll
;         for (int a = 0; a < 2; ++a)
; #pragma unroll
;             for (int b = 0; b < 2; ++b)
; #pragma unroll
;                 for (int m = 0; m < 4; ++m)
; #pragma unroll
;                     for (int n = 0; n < 2; ++n) acc[a][b][m][n] = (f32x4){0.f, 0.f, 0.f, 0.f};
.LBB0_673:
	s_add_u32 s40, s40, 0x80080
	s_addc_u32 s41, s41, 0
	s_add_u32 s35, s42, 0x100
	v_mov_b32_e32 v4, 0
	s_addc_u32 s62, s43, 0
	s_mov_b32 s63, -2
	v_mov_b32_e32 v5, v4
	v_mov_b32_e32 v6, v4
	v_mov_b32_e32 v7, v4
	v_mov_b32_e32 v8, v4
	v_mov_b32_e32 v9, v4
	v_mov_b32_e32 v10, v4
	v_mov_b32_e32 v11, v4
	v_mov_b32_e32 v16, v4
	v_mov_b32_e32 v17, v4
	v_mov_b32_e32 v18, v4
	v_mov_b32_e32 v19, v4
	v_mov_b32_e32 v24, v4
	v_mov_b32_e32 v25, v4
	v_mov_b32_e32 v26, v4
	v_mov_b32_e32 v27, v4
	v_mov_b32_e32 v32, v4
	v_mov_b32_e32 v33, v4
	v_mov_b32_e32 v34, v4
	v_mov_b32_e32 v35, v4
	v_mov_b32_e32 v40, v4
	v_mov_b32_e32 v41, v4
	v_mov_b32_e32 v42, v4
	v_mov_b32_e32 v43, v4
	v_mov_b32_e32 v48, v4
	v_mov_b32_e32 v49, v4
	v_mov_b32_e32 v50, v4
	v_mov_b32_e32 v51, v4
	v_mov_b32_e32 v56, v4
	v_mov_b32_e32 v57, v4
	v_mov_b32_e32 v58, v4
	v_mov_b32_e32 v59, v4
	v_mov_b32_e32 v12, v4
	v_mov_b32_e32 v13, v4
	v_mov_b32_e32 v14, v4
	v_mov_b32_e32 v15, v4
	v_mov_b32_e32 v20, v4
	v_mov_b32_e32 v21, v4
	v_mov_b32_e32 v22, v4
	v_mov_b32_e32 v23, v4
	v_mov_b32_e32 v28, v4
	v_mov_b32_e32 v29, v4
	v_mov_b32_e32 v30, v4
	v_mov_b32_e32 v31, v4
	v_mov_b32_e32 v36, v4
	v_mov_b32_e32 v37, v4
	v_mov_b32_e32 v38, v4
	v_mov_b32_e32 v39, v4
	v_mov_b32_e32 v44, v4
	v_mov_b32_e32 v45, v4
	v_mov_b32_e32 v46, v4
	v_mov_b32_e32 v47, v4
	v_mov_b32_e32 v52, v4
	v_mov_b32_e32 v53, v4
	v_mov_b32_e32 v54, v4
	v_mov_b32_e32 v55, v4
	v_mov_b32_e32 v60, v4
	v_mov_b32_e32 v61, v4
	v_mov_b32_e32 v62, v4
	v_mov_b32_e32 v63, v4
	v_mov_b32_e32 v64, v4
	v_mov_b32_e32 v65, v4
	v_mov_b32_e32 v66, v4
	v_mov_b32_e32 v67, v4
	v_mov_b32_e32 v68, v4
	v_mov_b32_e32 v69, v4
	v_mov_b32_e32 v70, v4
	v_mov_b32_e32 v71, v4
	v_mov_b32_e32 v72, v4
	v_mov_b32_e32 v73, v4
	v_mov_b32_e32 v74, v4
	v_mov_b32_e32 v75, v4
	v_mov_b32_e32 v80, v4
	v_mov_b32_e32 v81, v4
	v_mov_b32_e32 v82, v4
	v_mov_b32_e32 v83, v4
	v_mov_b32_e32 v88, v4
	v_mov_b32_e32 v89, v4
	v_mov_b32_e32 v90, v4
	v_mov_b32_e32 v91, v4
	v_mov_b32_e32 v96, v4
	v_mov_b32_e32 v97, v4
	v_mov_b32_e32 v98, v4
	v_mov_b32_e32 v99, v4
	v_mov_b32_e32 v104, v4
	v_mov_b32_e32 v105, v4
	v_mov_b32_e32 v106, v4
	v_mov_b32_e32 v107, v4
	v_mov_b32_e32 v112, v4
	v_mov_b32_e32 v113, v4
	v_mov_b32_e32 v114, v4
	v_mov_b32_e32 v115, v4
	v_mov_b32_e32 v120, v4
	v_mov_b32_e32 v121, v4
	v_mov_b32_e32 v122, v4
	v_mov_b32_e32 v123, v4
	v_mov_b32_e32 v76, v4
	v_mov_b32_e32 v77, v4
	v_mov_b32_e32 v78, v4
	v_mov_b32_e32 v79, v4
	v_mov_b32_e32 v84, v4
	v_mov_b32_e32 v85, v4
	v_mov_b32_e32 v86, v4
	v_mov_b32_e32 v87, v4
	v_mov_b32_e32 v92, v4
	v_mov_b32_e32 v93, v4
	v_mov_b32_e32 v94, v4
	v_mov_b32_e32 v95, v4
	v_mov_b32_e32 v100, v4
	v_mov_b32_e32 v101, v4
	v_mov_b32_e32 v102, v4
	v_mov_b32_e32 v103, v4
	v_mov_b32_e32 v108, v4
	v_mov_b32_e32 v109, v4
	v_mov_b32_e32 v110, v4
	v_mov_b32_e32 v111, v4
	v_mov_b32_e32 v116, v4
	v_mov_b32_e32 v117, v4
	v_mov_b32_e32 v118, v4
	v_mov_b32_e32 v119, v4
	v_mov_b32_e32 v124, v4
	v_mov_b32_e32 v125, v4
	v_mov_b32_e32 v126, v4
	v_mov_b32_e32 v127, v4
	v_mov_b32_e32 v128, v4
	v_mov_b32_e32 v129, v4
	v_mov_b32_e32 v130, v4
	v_mov_b32_e32 v131, v4
	v_add_u32_e32 v249, 0x10000, v173
	ds_read_b128 v[132:135], v249
	ds_read_b128 v[136:139], v249 offset:1024
	ds_read_b128 v[140:143], v249 offset:2048
	ds_read_b128 v[144:147], v249 offset:3072
	.p2align 6
	s_nop 0
.LBB0_674:
	s_add_u32 s42, s40, 0xfff80080
	s_addc_u32 s43, s41, -1
	s_add_i32 s64, 0, 0x10000
	s_cmp_eq_u32 s63, 28
	s_cselect_b32 s45, s5, s43
	s_cselect_b32 s44, s4, s42
	s_cselect_b32 s43, s37, s62
	s_cselect_b32 s42, s36, s35
	s_add_i32 s66, 0, 0x14000
	ds_read_b128 v[158:161], v249 offset:16384
	ds_read_b128 v[174:177], v249 offset:17408
	ds_read_b128 v[206:209], v249 offset:18432
	ds_read_b128 v[210:213], v249 offset:19456
	s_add_i32 m0, s39, 0xc000
	ds_read_b128 v[214:217], v204
	ds_read_b128 v[218:221], v204 offset:1024
	ds_read_b128 v[222:225], v204 offset:2048
	ds_read_b128 v[226:229], v204 offset:3072
	ds_read_b128 v[230:233], v204 offset:4096
	ds_read_b128 v[234:237], v204 offset:5120
	ds_read_b128 v[238:241], v204 offset:6144
	ds_read_b128 v[242:245], v204 offset:7168
	global_load_lds_dwordx4 v154, s[40:41]
	s_add_i32 m0, s39, 0xe000
	s_nop 0
	global_load_lds_dwordx4 v156, s[40:41]
	s_nop 0
	s_waitcnt vmcnt(8) lgkmcnt(0)
	s_barrier
	s_setprio 0
	s_waitcnt lgkmcnt(0)
	v_mfma_f32_16x16x32_bf16 v[128:131], v[132:135], v[214:217], v[128:131]
	v_mfma_f32_16x16x32_bf16 v[124:127], v[140:143], v[214:217], v[124:127]
	v_mfma_f32_16x16x32_bf16 v[116:119], v[132:135], v[222:225], v[116:119]
	v_mfma_f32_16x16x32_bf16 v[108:111], v[140:143], v[222:225], v[108:111]
	v_mfma_f32_16x16x32_bf16 v[100:103], v[132:135], v[230:233], v[100:103]
	v_mfma_f32_16x16x32_bf16 v[92:95], v[140:143], v[230:233], v[92:95]
	v_mfma_f32_16x16x32_bf16 v[84:87], v[132:135], v[238:241], v[84:87]
	v_mfma_f32_16x16x32_bf16 v[76:79], v[140:143], v[238:241], v[76:79]
	v_mfma_f32_16x16x32_bf16 v[128:131], v[136:139], v[218:221], v[128:131]
	v_mfma_f32_16x16x32_bf16 v[124:127], v[144:147], v[218:221], v[124:127]
	v_mfma_f32_16x16x32_bf16 v[116:119], v[136:139], v[226:229], v[116:119]
	v_mfma_f32_16x16x32_bf16 v[108:111], v[144:147], v[226:229], v[108:111]
	v_mfma_f32_16x16x32_bf16 v[100:103], v[136:139], v[234:237], v[100:103]
	v_mfma_f32_16x16x32_bf16 v[92:95], v[144:147], v[234:237], v[92:95]
	v_mfma_f32_16x16x32_bf16 v[84:87], v[136:139], v[242:245], v[84:87]
	v_mfma_f32_16x16x32_bf16 v[76:79], v[144:147], v[242:245], v[76:79]
	v_mfma_f32_16x16x32_bf16 v[120:123], v[158:161], v[214:217], v[120:123]
	v_mfma_f32_16x16x32_bf16 v[112:115], v[206:209], v[214:217], v[112:115]
	v_mfma_f32_16x16x32_bf16 v[104:107], v[158:161], v[222:225], v[104:107]
	v_mfma_f32_16x16x32_bf16 v[96:99], v[206:209], v[222:225], v[96:99]
	v_mfma_f32_16x16x32_bf16 v[88:91], v[158:161], v[230:233], v[88:91]
	v_mfma_f32_16x16x32_bf16 v[80:83], v[206:209], v[230:233], v[80:83]
	v_mfma_f32_16x16x32_bf16 v[72:75], v[158:161], v[238:241], v[72:75]
	v_mfma_f32_16x16x32_bf16 v[68:71], v[206:209], v[238:241], v[68:71]
	v_mfma_f32_16x16x32_bf16 v[120:123], v[174:177], v[218:221], v[120:123]
	v_mfma_f32_16x16x32_bf16 v[112:115], v[210:213], v[218:221], v[112:115]
	v_mfma_f32_16x16x32_bf16 v[104:107], v[174:177], v[226:229], v[104:107]
	v_mfma_f32_16x16x32_bf16 v[96:99], v[210:213], v[226:229], v[96:99]
	v_mfma_f32_16x16x32_bf16 v[88:91], v[174:177], v[234:237], v[88:91]
	v_mfma_f32_16x16x32_bf16 v[80:83], v[210:213], v[234:237], v[80:83]
	v_mfma_f32_16x16x32_bf16 v[72:75], v[174:177], v[242:245], v[72:75]
	v_mfma_f32_16x16x32_bf16 v[68:71], v[210:213], v[242:245], v[68:71]
	s_setprio 3
	s_barrier
; #define PG8_STAGE(bufoff, gbase, voff) do { _Pragma("unroll") for (int _i = 0; _i < 2; ++_i) \
;         __builtin_amdgcn_global_load_lds((const unsigned*)((const char*)(gbase) + (voff)[_i]), (PG8_LAS unsigned*)(lds + (bufoff) + ldsw + _i * 8192), 16, 0, 0); } while (0)
; #define PG8_LDA(dst, b, h) do { _Pragma("unroll") for (int m = 0; m < 4; ++m) _Pragma("unroll") for (int k = 0; k < 2; ++k) dst[m][k] = *(const PG8_LAS bf16x8*)(lds + PG8_SA(b, h) + aoff + m * 2048 + k * 1024); } while (0)
; #define PG8_LDB(dst, b, h) do { _Pragma("unroll") for (int n = 0; n < 2; ++n) _Pragma("unroll") for (int k = 0; k < 2; ++k) dst[n][k] = *(const PG8_LAS bf16x8*)(lds + PG8_SB(b, h) + boff + n * 2048 + k * 1024); } while (0)
; #define PG8_MMA(ai, bj, At, Bt) do { __builtin_amdgcn_s_setprio(1); _Pragma("unroll") for (int m = 0; m < 4; ++m) _Pragma("unroll") for (int n = 0; n < 2; ++n) _Pragma("unroll") for (int k = 0; k < 2; ++k) \
;         acc[ai][bj][m][n] = __builtin_amdgcn_mfma_f32_16x16x32_bf16(Bt[n][k], At[m][k], acc[ai][bj][m][n], 0, 0, 0); __builtin_amdgcn_s_setprio(0); } while (0)
; #define PG8_WAIT_V(n) asm volatile("s_waitcnt vmcnt(" #n ")" ::: "memory")
; #define PG8_WAIT_L(n) asm volatile("s_waitcnt lgkmcnt(" #n ")" ::: "memory")
; #define PG8_BAR __builtin_amdgcn_s_barrier()
; #define PG8_SCHED __builtin_amdgcn_sched_barrier(0)
; template <class Epi, class Sched, bool ALIGN_EPI = false, bool SP2 = false>
; __device__ __forceinline__ void gemm_phase(PG8_LAS unsigned char* lds, const Gemm g, const Sched& S, const Epi& E) {
;     ...
;             PG8_LDA(At, 0, 1); PG8_STAGE(PG8_SB(0, 0), b2, voffB); PG8_STAGE(PG8_SB(0, 1), b2 + hstep, voffB); PG8_STAGE(PG8_SA(0, 0), a2, voffA);
;             PG8_WAIT_V(8); PG8_WAIT_L(0); PG8_BAR; PG8_MMA(1, 0, At, B0); PG8_MMA(1, 1, At, B1); PG8_BAR; PG8_SCHED;
;             PG8_LDB(B0, 1, 0); PG8_LDB(B1, 1, 1); PG8_SCHED; PG8_LDA(At, 1, 0); PG8_STAGE(PG8_SA(0, 1), a2 + hstep, voffA);
	s_add_i32 s64, s64, s46
	s_mov_b32 m0, s64
	ds_read_b128 v[214:217], v204 offset:16384
	ds_read_b128 v[218:221], v204 offset:17408
	ds_read_b128 v[222:225], v204 offset:18432
	ds_read_b128 v[226:229], v204 offset:19456
	ds_read_b128 v[230:233], v204 offset:20480
	ds_read_b128 v[234:237], v204 offset:21504
	ds_read_b128 v[238:241], v204 offset:22528
	ds_read_b128 v[242:245], v204 offset:23552
	global_load_lds_dwordx4 v2, s[42:43]
	s_add_i32 m0, s64, 0x2000
	s_add_u32 s64, s42, 0x80000
	s_addc_u32 s65, s43, 0
	s_add_i32 s66, s66, s46
	global_load_lds_dwordx4 v148, s[42:43]
	s_mov_b32 m0, s66
	s_nop 0
	global_load_lds_dwordx4 v2, s[64:65]
	s_add_i32 m0, s66, 0x2000
	s_nop 0
	global_load_lds_dwordx4 v148, s[64:65]
	s_mov_b32 m0, s39
	s_nop 0
	global_load_lds_dwordx4 v152, s[44:45]
	s_mov_b32 m0, s51
	s_nop 0
	global_load_lds_dwordx4 v150, s[44:45]
	s_nop 0
	s_waitcnt vmcnt(8) lgkmcnt(0)
	s_barrier
	s_setprio 0
	s_waitcnt lgkmcnt(0)
	v_mfma_f32_16x16x32_bf16 v[64:67], v[132:135], v[214:217], v[64:67]
	v_mfma_f32_16x16x32_bf16 v[60:63], v[140:143], v[214:217], v[60:63]
	v_mfma_f32_16x16x32_bf16 v[52:55], v[132:135], v[222:225], v[52:55]
	v_mfma_f32_16x16x32_bf16 v[44:47], v[140:143], v[222:225], v[44:47]
	v_mfma_f32_16x16x32_bf16 v[36:39], v[132:135], v[230:233], v[36:39]
	v_mfma_f32_16x16x32_bf16 v[28:31], v[140:143], v[230:233], v[28:31]
	v_mfma_f32_16x16x32_bf16 v[20:23], v[132:135], v[238:241], v[20:23]
	v_mfma_f32_16x16x32_bf16 v[12:15], v[140:143], v[238:241], v[12:15]
	v_mfma_f32_16x16x32_bf16 v[64:67], v[136:139], v[218:221], v[64:67]
	v_mfma_f32_16x16x32_bf16 v[60:63], v[144:147], v[218:221], v[60:63]
	v_mfma_f32_16x16x32_bf16 v[52:55], v[136:139], v[226:229], v[52:55]
	v_mfma_f32_16x16x32_bf16 v[44:47], v[144:147], v[226:229], v[44:47]
	v_mfma_f32_16x16x32_bf16 v[36:39], v[136:139], v[234:237], v[36:39]
	v_mfma_f32_16x16x32_bf16 v[28:31], v[144:147], v[234:237], v[28:31]
	v_mfma_f32_16x16x32_bf16 v[20:23], v[136:139], v[242:245], v[20:23]
	v_mfma_f32_16x16x32_bf16 v[12:15], v[144:147], v[242:245], v[12:15]
	v_mfma_f32_16x16x32_bf16 v[56:59], v[158:161], v[214:217], v[56:59]
	ds_read_b128 v[132:135], v249 offset:32768
	v_mfma_f32_16x16x32_bf16 v[48:51], v[206:209], v[214:217], v[48:51]
	ds_read_b128 v[136:139], v249 offset:33792
	v_mfma_f32_16x16x32_bf16 v[40:43], v[158:161], v[222:225], v[40:43]
	ds_read_b128 v[140:143], v249 offset:34816
	v_mfma_f32_16x16x32_bf16 v[32:35], v[206:209], v[222:225], v[32:35]
	ds_read_b128 v[144:147], v249 offset:35840
	v_mfma_f32_16x16x32_bf16 v[24:27], v[158:161], v[230:233], v[24:27]
	v_mfma_f32_16x16x32_bf16 v[16:19], v[206:209], v[230:233], v[16:19]
	v_mfma_f32_16x16x32_bf16 v[8:11], v[158:161], v[238:241], v[8:11]
	v_mfma_f32_16x16x32_bf16 v[4:7], v[206:209], v[238:241], v[4:7]
	v_mfma_f32_16x16x32_bf16 v[56:59], v[174:177], v[218:221], v[56:59]
	v_mfma_f32_16x16x32_bf16 v[48:51], v[210:213], v[218:221], v[48:51]
	v_mfma_f32_16x16x32_bf16 v[40:43], v[174:177], v[226:229], v[40:43]
	v_mfma_f32_16x16x32_bf16 v[32:35], v[210:213], v[226:229], v[32:35]
	v_mfma_f32_16x16x32_bf16 v[24:27], v[174:177], v[234:237], v[24:27]
	v_mfma_f32_16x16x32_bf16 v[16:19], v[210:213], v[234:237], v[16:19]
	v_mfma_f32_16x16x32_bf16 v[8:11], v[174:177], v[242:245], v[8:11]
	v_mfma_f32_16x16x32_bf16 v[4:7], v[210:213], v[242:245], v[4:7]
	s_setprio 3
	s_barrier
	s_add_i32 s64, 0, 0x18000
	s_add_i32 s65, 0, 0x1c000
	ds_read_b128 v[158:161], v249 offset:49152
	ds_read_b128 v[174:177], v249 offset:50176
	ds_read_b128 v[206:209], v249 offset:51200
	ds_read_b128 v[210:213], v249 offset:52224
	s_add_u32 s100, s44, 0x80
	s_addc_u32 s101, s45, 0
	s_add_u32 s44, s44, 0x80000
	s_addc_u32 s45, s45, 0
	s_mov_b32 m0, s52
	ds_read_b128 v[214:217], v204 offset:32768
	ds_read_b128 v[218:221], v204 offset:33792
	ds_read_b128 v[222:225], v204 offset:34816
	ds_read_b128 v[226:229], v204 offset:35840
	ds_read_b128 v[230:233], v204 offset:36864
	ds_read_b128 v[234:237], v204 offset:37888
	ds_read_b128 v[238:241], v204 offset:38912
	ds_read_b128 v[242:245], v204 offset:39936
	global_load_lds_dwordx4 v152, s[44:45]
	s_mov_b32 m0, s53
	s_nop 0
	global_load_lds_dwordx4 v150, s[44:45]
	s_nop 0
	s_waitcnt vmcnt(8) lgkmcnt(0)
	s_barrier
; #define PG8_STAGE(bufoff, gbase, voff) do { _Pragma("unroll") for (int _i = 0; _i < 2; ++_i) \
;         __builtin_amdgcn_global_load_lds((const unsigned*)((const char*)(gbase) + (voff)[_i]), (PG8_LAS unsigned*)(lds + (bufoff) + ldsw + _i * 8192), 16, 0, 0); } while (0)
; #define PG8_LDA(dst, b, h) do { _Pragma("unroll") for (int m = 0; m < 4; ++m) _Pragma("unroll") for (int k = 0; k < 2; ++k) dst[m][k] = *(const PG8_LAS bf16x8*)(lds + PG8_SA(b, h) + aoff + m * 2048 + k * 1024); } while (0)
; #define PG8_MMA(ai, bj, At, Bt) do { __builtin_amdgcn_s_setprio(1); _Pragma("unroll") for (int m = 0; m < 4; ++m) _Pragma("unroll") for (int n = 0; n < 2; ++n) _Pragma("unroll") for (int k = 0; k < 2; ++k) \
;         acc[ai][bj][m][n] = __builtin_amdgcn_mfma_f32_16x16x32_bf16(Bt[n][k], At[m][k], acc[ai][bj][m][n], 0, 0, 0); __builtin_amdgcn_s_setprio(0); } while (0)
; #define PG8_WAIT_V(n) asm volatile("s_waitcnt vmcnt(" #n ")" ::: "memory")
; #define PG8_WAIT_L(n) asm volatile("s_waitcnt lgkmcnt(" #n ")" ::: "memory")
; #define PG8_BAR __builtin_amdgcn_s_barrier()
; #define PG8_SCHED __builtin_amdgcn_sched_barrier(0)
; template <class Epi, class Sched, bool ALIGN_EPI = false, bool SP2 = false>
; __device__ __forceinline__ void gemm_phase(PG8_LAS unsigned char* lds, const Gemm g, const Sched& S, const Epi& E) {
;     ...
;             PG8_WAIT_V(8); PG8_WAIT_L(0); PG8_BAR; PG8_MMA(0, 0, At, B0); PG8_MMA(0, 1, At, B1); PG8_BAR; PG8_SCHED;
;             PG8_LDA(At, 1, 1); PG8_STAGE(PG8_SB(1, 0), b3, voffB); PG8_STAGE(PG8_SB(1, 1), b3 + hstep, voffB); PG8_STAGE(PG8_SA(1, 0), a3, voffA);
;             PG8_WAIT_V(8); PG8_WAIT_L(0); PG8_BAR; PG8_MMA(1, 0, At, B0); PG8_MMA(1, 1, At, B1); PG8_BAR; PG8_SCHED;
	s_setprio 0
	s_waitcnt lgkmcnt(0)
	v_mfma_f32_16x16x32_bf16 v[128:131], v[132:135], v[214:217], v[128:131]
	v_mfma_f32_16x16x32_bf16 v[124:127], v[140:143], v[214:217], v[124:127]
	v_mfma_f32_16x16x32_bf16 v[116:119], v[132:135], v[222:225], v[116:119]
	v_mfma_f32_16x16x32_bf16 v[108:111], v[140:143], v[222:225], v[108:111]
	v_mfma_f32_16x16x32_bf16 v[100:103], v[132:135], v[230:233], v[100:103]
	v_mfma_f32_16x16x32_bf16 v[92:95], v[140:143], v[230:233], v[92:95]
	v_mfma_f32_16x16x32_bf16 v[84:87], v[132:135], v[238:241], v[84:87]
	v_mfma_f32_16x16x32_bf16 v[76:79], v[140:143], v[238:241], v[76:79]
	v_mfma_f32_16x16x32_bf16 v[128:131], v[136:139], v[218:221], v[128:131]
	v_mfma_f32_16x16x32_bf16 v[124:127], v[144:147], v[218:221], v[124:127]
	v_mfma_f32_16x16x32_bf16 v[116:119], v[136:139], v[226:229], v[116:119]
	v_mfma_f32_16x16x32_bf16 v[108:111], v[144:147], v[226:229], v[108:111]
	v_mfma_f32_16x16x32_bf16 v[100:103], v[136:139], v[234:237], v[100:103]
	v_mfma_f32_16x16x32_bf16 v[92:95], v[144:147], v[234:237], v[92:95]
	v_mfma_f32_16x16x32_bf16 v[84:87], v[136:139], v[242:245], v[84:87]
	v_mfma_f32_16x16x32_bf16 v[76:79], v[144:147], v[242:245], v[76:79]
	v_mfma_f32_16x16x32_bf16 v[120:123], v[158:161], v[214:217], v[120:123]
	v_mfma_f32_16x16x32_bf16 v[112:115], v[206:209], v[214:217], v[112:115]
	v_mfma_f32_16x16x32_bf16 v[104:107], v[158:161], v[222:225], v[104:107]
	v_mfma_f32_16x16x32_bf16 v[96:99], v[206:209], v[222:225], v[96:99]
	v_mfma_f32_16x16x32_bf16 v[88:91], v[158:161], v[230:233], v[88:91]
	v_mfma_f32_16x16x32_bf16 v[80:83], v[206:209], v[230:233], v[80:83]
	v_mfma_f32_16x16x32_bf16 v[72:75], v[158:161], v[238:241], v[72:75]
	v_mfma_f32_16x16x32_bf16 v[68:71], v[206:209], v[238:241], v[68:71]
	v_mfma_f32_16x16x32_bf16 v[120:123], v[174:177], v[218:221], v[120:123]
	v_mfma_f32_16x16x32_bf16 v[112:115], v[210:213], v[218:221], v[112:115]
	v_mfma_f32_16x16x32_bf16 v[104:107], v[174:177], v[226:229], v[104:107]
	v_mfma_f32_16x16x32_bf16 v[96:99], v[210:213], v[226:229], v[96:99]
	v_mfma_f32_16x16x32_bf16 v[88:91], v[174:177], v[234:237], v[88:91]
	v_mfma_f32_16x16x32_bf16 v[80:83], v[210:213], v[234:237], v[80:83]
	v_mfma_f32_16x16x32_bf16 v[72:75], v[174:177], v[242:245], v[72:75]
	v_mfma_f32_16x16x32_bf16 v[68:71], v[210:213], v[242:245], v[68:71]
	s_setprio 3
	s_barrier
	s_add_i32 s44, s64, s46
	s_add_i32 m0, s44, 0xffffff80
	ds_read_b128 v[214:217], v204 offset:49152
	ds_read_b128 v[218:221], v204 offset:50176
	ds_read_b128 v[222:225], v204 offset:51200
	ds_read_b128 v[226:229], v204 offset:52224
	ds_read_b128 v[230:233], v204 offset:53248
	ds_read_b128 v[234:237], v204 offset:54272
	ds_read_b128 v[238:241], v204 offset:55296
	ds_read_b128 v[242:245], v204 offset:56320
	global_load_lds_dwordx4 v2, s[42:43] offset:128
	s_add_i32 m0, s44, 0x1f80
	s_add_i32 s44, s65, s46
	global_load_lds_dwordx4 v148, s[42:43] offset:128
	s_add_u32 s42, s42, 0x80080
	s_addc_u32 s43, s43, 0
	s_mov_b32 m0, s44
	s_nop 0
	global_load_lds_dwordx4 v2, s[42:43]
	s_add_i32 m0, s44, 0x2000
	s_nop 0
	global_load_lds_dwordx4 v148, s[42:43]
	s_mov_b32 m0, s54
	s_nop 0
	global_load_lds_dwordx4 v152, s[100:101]
	s_mov_b32 m0, s55
	s_nop 0
	global_load_lds_dwordx4 v150, s[100:101]
	s_waitcnt vmcnt(8) lgkmcnt(0)
	s_barrier
	s_setprio 0
	s_waitcnt lgkmcnt(0)
	v_mfma_f32_16x16x32_bf16 v[64:67], v[132:135], v[214:217], v[64:67]
	v_mfma_f32_16x16x32_bf16 v[60:63], v[140:143], v[214:217], v[60:63]
	v_mfma_f32_16x16x32_bf16 v[52:55], v[132:135], v[222:225], v[52:55]
	v_mfma_f32_16x16x32_bf16 v[44:47], v[140:143], v[222:225], v[44:47]
	v_mfma_f32_16x16x32_bf16 v[36:39], v[132:135], v[230:233], v[36:39]
	v_mfma_f32_16x16x32_bf16 v[28:31], v[140:143], v[230:233], v[28:31]
	v_mfma_f32_16x16x32_bf16 v[20:23], v[132:135], v[238:241], v[20:23]
	v_mfma_f32_16x16x32_bf16 v[12:15], v[140:143], v[238:241], v[12:15]
	v_mfma_f32_16x16x32_bf16 v[64:67], v[136:139], v[218:221], v[64:67]
	v_mfma_f32_16x16x32_bf16 v[60:63], v[144:147], v[218:221], v[60:63]
	v_mfma_f32_16x16x32_bf16 v[52:55], v[136:139], v[226:229], v[52:55]
	v_mfma_f32_16x16x32_bf16 v[44:47], v[144:147], v[226:229], v[44:47]
	v_mfma_f32_16x16x32_bf16 v[36:39], v[136:139], v[234:237], v[36:39]
	v_mfma_f32_16x16x32_bf16 v[28:31], v[144:147], v[234:237], v[28:31]
	v_mfma_f32_16x16x32_bf16 v[20:23], v[136:139], v[242:245], v[20:23]
	v_mfma_f32_16x16x32_bf16 v[12:15], v[144:147], v[242:245], v[12:15]
	v_mfma_f32_16x16x32_bf16 v[56:59], v[158:161], v[214:217], v[56:59]
	ds_read_b128 v[132:135], v249
	v_mfma_f32_16x16x32_bf16 v[48:51], v[206:209], v[214:217], v[48:51]
	ds_read_b128 v[136:139], v249 offset:1024
	v_mfma_f32_16x16x32_bf16 v[40:43], v[158:161], v[222:225], v[40:43]
	ds_read_b128 v[140:143], v249 offset:2048
	v_mfma_f32_16x16x32_bf16 v[32:35], v[206:209], v[222:225], v[32:35]
	ds_read_b128 v[144:147], v249 offset:3072
	v_mfma_f32_16x16x32_bf16 v[24:27], v[158:161], v[230:233], v[24:27]
	v_mfma_f32_16x16x32_bf16 v[16:19], v[206:209], v[230:233], v[16:19]
	v_mfma_f32_16x16x32_bf16 v[8:11], v[158:161], v[238:241], v[8:11]
	v_mfma_f32_16x16x32_bf16 v[4:7], v[206:209], v[238:241], v[4:7]
	v_mfma_f32_16x16x32_bf16 v[56:59], v[174:177], v[218:221], v[56:59]
	v_mfma_f32_16x16x32_bf16 v[48:51], v[210:213], v[218:221], v[48:51]
	v_mfma_f32_16x16x32_bf16 v[40:43], v[174:177], v[226:229], v[40:43]
	v_mfma_f32_16x16x32_bf16 v[32:35], v[210:213], v[226:229], v[32:35]
	v_mfma_f32_16x16x32_bf16 v[24:27], v[174:177], v[234:237], v[24:27]
	v_mfma_f32_16x16x32_bf16 v[16:19], v[210:213], v[234:237], v[16:19]
	v_mfma_f32_16x16x32_bf16 v[8:11], v[174:177], v[242:245], v[8:11]
	v_mfma_f32_16x16x32_bf16 v[4:7], v[210:213], v[242:245], v[4:7]
	s_setprio 3
	s_barrier
	s_add_i32 s63, s63, 2
	s_add_u32 s40, s40, 0x100
	s_addc_u32 s41, s41, 0
	s_add_u32 s35, s35, 0x100
	s_addc_u32 s62, s62, 0
	s_cmp_gt_u32 s63, 29
	s_cbranch_scc0 .LBB0_674
	s_and_b64 vcc, exec, s[30:31]
	s_cbranch_vccz .LBB0_677
	s_barrier

; #define PG8_STAGE(bufoff, gbase, voff) do { _Pragma("unroll") for (int _i = 0; _i < 2; ++_i) \
;         __builtin_amdgcn_global_load_lds((const unsigned*)((const char*)(gbase) + (voff)[_i]), (PG8_LAS unsigned*)(lds + (bufoff) + ldsw + _i * 8192), 16, 0, 0); } while (0)
; #define PG8_LDA(dst, b, h) do { _Pragma("unroll") for (int m = 0; m < 4; ++m) _Pragma("unroll") for (int k = 0; k < 2; ++k) dst[m][k] = *(const PG8_LAS bf16x8*)(lds + PG8_SA(b, h) + aoff + m * 2048 + k * 1024); } while (0)
; #define PG8_LDB(dst, b, h) do { _Pragma("unroll") for (int n = 0; n < 2; ++n) _Pragma("unroll") for (int k = 0; k < 2; ++k) dst[n][k] = *(const PG8_LAS bf16x8*)(lds + PG8_SB(b, h) + boff + n * 2048 + k * 1024); } while (0)
; #define PG8_MMA(ai, bj, At, Bt) do { __builtin_amdgcn_s_setprio(1); _Pragma("unroll") for (int m = 0; m < 4; ++m) _Pragma("unroll") for (int n = 0; n < 2; ++n) _Pragma("unroll") for (int k = 0; k < 2; ++k) \
;         acc[ai][bj][m][n] = __builtin_amdgcn_mfma_f32_16x16x32_bf16(Bt[n][k], At[m][k], acc[ai][bj][m][n], 0, 0, 0); __builtin_amdgcn_s_setprio(0); } while (0)
; #define PG8_WAIT_V(n) asm volatile("s_waitcnt vmcnt(" #n ")" ::: "memory")
; #define PG8_WAIT_L(n) asm volatile("s_waitcnt lgkmcnt(" #n ")" ::: "memory")
; #define PG8_BAR __builtin_amdgcn_s_barrier()
; #define PG8_SCHED __builtin_amdgcn_sched_barrier(0)
; template <class Epi, class Sched, bool ALIGN_EPI = false, bool SP2 = false>
; __device__ __forceinline__ void gemm_phase(PG8_LAS unsigned char* lds, const Gemm g, const Sched& S, const Epi& E) {
;     ...
;         for (int t = 0; t < nt; t += 2) {
;             const bool last = (t == nt - 2);
;             const char* a1 = cA + (size_t)(t + 1) * kstep;
;             const char* a2 = last ? nA : cA + (size_t)(t + 2) * kstep; const char* b2 = last ? nB : cB + (size_t)(t + 2) * kstep;
;             const char* a3 = a2 + kstep; const char* b3 = b2 + kstep;
;             if (last && has_next) S.a_ready(nxt);
;             if constexpr (SP2) {
;             PG8_LDB(B0, 0, 0); PG8_LDB(B1, 0, 1); PG8_SCHED; PG8_LDA(At, 0, 0); PG8_STAGE(PG8_SA(1, 1), a1 + hstep, voffA);
;             PG8_WAIT_V(8); PG8_WAIT_L(0); PG8_BAR; PG8_MMA(0, 0, At, B0); PG8_MMA(0, 1, At, B1); PG8_BAR; PG8_SCHED;
.LBB0_2095:
	s_add_u32 s40, s40, 0x40080
	s_addc_u32 s41, s41, 0
	s_add_u32 s11, s42, 0x100
	s_addc_u32 s13, s43, 0
	s_mov_b32 s26, -2
	v_add_u32_e32 v175, 0x10000, v173
	ds_read_b128 v[134:137], v175
	ds_read_b128 v[138:141], v175 offset:1024
	ds_read_b128 v[154:157], v175 offset:2048
	ds_read_b128 v[158:161], v175 offset:3072
	.p2align 6
	s_nop 0
.LBB0_2096:
	s_add_u32 s27, s40, 0xfffc0080
	s_addc_u32 s29, s41, -1
	s_add_i32 s31, 0, 0x10000
	s_cmp_eq_u32 s26, 12
	s_cselect_b32 s45, s1, s29
	s_cselect_b32 s44, s0, s27
	s_cselect_b32 s43, s35, s13
	s_cselect_b32 s42, s34, s11
	s_add_i32 s27, 0, 0x14000
	ds_read_b128 v[178:181], v175 offset:16384
	ds_read_b128 v[204:207], v175 offset:17408
	ds_read_b128 v[208:211], v175 offset:18432
	ds_read_b128 v[212:215], v175 offset:19456
	s_add_i32 m0, s55, 0xc000
	ds_read_b128 v[216:219], v177
	ds_read_b128 v[220:223], v177 offset:1024
	ds_read_b128 v[224:227], v177 offset:2048
	ds_read_b128 v[228:231], v177 offset:3072
	ds_read_b128 v[232:235], v177 offset:4096
	ds_read_b128 v[236:239], v177 offset:5120
	ds_read_b128 v[240:243], v177 offset:6144
	ds_read_b128 v[244:247], v177 offset:7168
	global_load_lds_dwordx4 v150, s[40:41]
	s_add_i32 m0, s55, 0xe000
	s_nop 0
	global_load_lds_dwordx4 v152, s[40:41]
	s_nop 0
	s_waitcnt vmcnt(8) lgkmcnt(0)
	s_barrier
	s_setprio 0
	s_waitcnt lgkmcnt(0)
	v_mfma_f32_16x16x32_bf16 v[130:133], v[134:137], v[216:219], v[130:133]
	v_mfma_f32_16x16x32_bf16 v[126:129], v[154:157], v[216:219], v[126:129]
	v_mfma_f32_16x16x32_bf16 v[122:125], v[134:137], v[224:227], v[122:125]
	v_mfma_f32_16x16x32_bf16 v[118:121], v[154:157], v[224:227], v[118:121]
	v_mfma_f32_16x16x32_bf16 v[114:117], v[134:137], v[232:235], v[114:117]
	v_mfma_f32_16x16x32_bf16 v[110:113], v[154:157], v[232:235], v[110:113]
	v_mfma_f32_16x16x32_bf16 v[106:109], v[134:137], v[240:243], v[106:109]
	v_mfma_f32_16x16x32_bf16 v[102:105], v[154:157], v[240:243], v[102:105]
	v_mfma_f32_16x16x32_bf16 v[130:133], v[138:141], v[220:223], v[130:133]
	v_mfma_f32_16x16x32_bf16 v[126:129], v[158:161], v[220:223], v[126:129]
	v_mfma_f32_16x16x32_bf16 v[122:125], v[138:141], v[228:231], v[122:125]
	v_mfma_f32_16x16x32_bf16 v[118:121], v[158:161], v[228:231], v[118:121]
	v_mfma_f32_16x16x32_bf16 v[114:117], v[138:141], v[236:239], v[114:117]
	v_mfma_f32_16x16x32_bf16 v[110:113], v[158:161], v[236:239], v[110:113]
	v_mfma_f32_16x16x32_bf16 v[106:109], v[138:141], v[244:247], v[106:109]
	v_mfma_f32_16x16x32_bf16 v[102:105], v[158:161], v[244:247], v[102:105]
	v_mfma_f32_16x16x32_bf16 v[98:101], v[178:181], v[216:219], v[98:101]
	v_mfma_f32_16x16x32_bf16 v[94:97], v[208:211], v[216:219], v[94:97]
	v_mfma_f32_16x16x32_bf16 v[90:93], v[178:181], v[224:227], v[90:93]
	v_mfma_f32_16x16x32_bf16 v[86:89], v[208:211], v[224:227], v[86:89]
	v_mfma_f32_16x16x32_bf16 v[82:85], v[178:181], v[232:235], v[82:85]
	v_mfma_f32_16x16x32_bf16 v[78:81], v[208:211], v[232:235], v[78:81]
	v_mfma_f32_16x16x32_bf16 v[74:77], v[178:181], v[240:243], v[74:77]
	v_mfma_f32_16x16x32_bf16 v[70:73], v[208:211], v[240:243], v[70:73]
	v_mfma_f32_16x16x32_bf16 v[98:101], v[204:207], v[220:223], v[98:101]
	v_mfma_f32_16x16x32_bf16 v[94:97], v[212:215], v[220:223], v[94:97]
	v_mfma_f32_16x16x32_bf16 v[90:93], v[204:207], v[228:231], v[90:93]
	v_mfma_f32_16x16x32_bf16 v[86:89], v[212:215], v[228:231], v[86:89]
	v_mfma_f32_16x16x32_bf16 v[82:85], v[204:207], v[236:239], v[82:85]
	v_mfma_f32_16x16x32_bf16 v[78:81], v[212:215], v[236:239], v[78:81]
	v_mfma_f32_16x16x32_bf16 v[74:77], v[204:207], v[244:247], v[74:77]
	v_mfma_f32_16x16x32_bf16 v[70:73], v[212:215], v[244:247], v[70:73]
	s_setprio 3
	s_barrier
	s_add_i32 s29, s31, s54
	s_mov_b32 m0, s29
	ds_read_b128 v[216:219], v177 offset:16384
	ds_read_b128 v[220:223], v177 offset:17408
	ds_read_b128 v[224:227], v177 offset:18432
	ds_read_b128 v[228:231], v177 offset:19456
	ds_read_b128 v[232:235], v177 offset:20480
	ds_read_b128 v[236:239], v177 offset:21504
	ds_read_b128 v[240:243], v177 offset:22528
	ds_read_b128 v[244:247], v177 offset:23552
	global_load_lds_dwordx4 v144, s[42:43]
	s_add_i32 m0, s29, 0x2000
	s_add_u32 s64, s42, 0x40000
	s_addc_u32 s65, s43, 0
	s_add_i32 s27, s27, s54
	global_load_lds_dwordx4 v148, s[42:43]
	s_mov_b32 m0, s27
	s_nop 0
	global_load_lds_dwordx4 v144, s[64:65]
	s_add_i32 m0, s27, 0x2000
	s_nop 0
	global_load_lds_dwordx4 v148, s[64:65]
	s_mov_b32 m0, s55
	s_nop 0
	global_load_lds_dwordx4 v142, s[44:45]
	s_mov_b32 m0, s56
	s_nop 0
	global_load_lds_dwordx4 v146, s[44:45]
	s_nop 0
	s_waitcnt vmcnt(8) lgkmcnt(0)
	s_barrier
; #define PG8_STAGE(bufoff, gbase, voff) do { _Pragma("unroll") for (int _i = 0; _i < 2; ++_i) \
;         __builtin_amdgcn_global_load_lds((const unsigned*)((const char*)(gbase) + (voff)[_i]), (PG8_LAS unsigned*)(lds + (bufoff) + ldsw + _i * 8192), 16, 0, 0); } while (0)
; #define PG8_LDA(dst, b, h) do { _Pragma("unroll") for (int m = 0; m < 4; ++m) _Pragma("unroll") for (int k = 0; k < 2; ++k) dst[m][k] = *(const PG8_LAS bf16x8*)(lds + PG8_SA(b, h) + aoff + m * 2048 + k * 1024); } while (0)
; #define PG8_LDB(dst, b, h) do { _Pragma("unroll") for (int n = 0; n < 2; ++n) _Pragma("unroll") for (int k = 0; k < 2; ++k) dst[n][k] = *(const PG8_LAS bf16x8*)(lds + PG8_SB(b, h) + boff + n * 2048 + k * 1024); } while (0)
; #define PG8_MMA(ai, bj, At, Bt) do { __builtin_amdgcn_s_setprio(1); _Pragma("unroll") for (int m = 0; m < 4; ++m) _Pragma("unroll") for (int n = 0; n < 2; ++n) _Pragma("unroll") for (int k = 0; k < 2; ++k) \
;         acc[ai][bj][m][n] = __builtin_amdgcn_mfma_f32_16x16x32_bf16(Bt[n][k], At[m][k], acc[ai][bj][m][n], 0, 0, 0); __builtin_amdgcn_s_setprio(0); } while (0)
; #define PG8_WAIT_V(n) asm volatile("s_waitcnt vmcnt(" #n ")" ::: "memory")
; #define PG8_WAIT_L(n) asm volatile("s_waitcnt lgkmcnt(" #n ")" ::: "memory")
; #define PG8_BAR __builtin_amdgcn_s_barrier()
; #define PG8_SCHED __builtin_amdgcn_sched_barrier(0)
; template <class Epi, class Sched, bool ALIGN_EPI = false, bool SP2 = false>
; __device__ __forceinline__ void gemm_phase(PG8_LAS unsigned char* lds, const Gemm g, const Sched& S, const Epi& E) {
;     ...
;             PG8_LDA(At, 0, 1); PG8_STAGE(PG8_SB(0, 0), b2, voffB); PG8_STAGE(PG8_SB(0, 1), b2 + hstep, voffB); PG8_STAGE(PG8_SA(0, 0), a2, voffA);
;             PG8_WAIT_V(8); PG8_WAIT_L(0); PG8_BAR; PG8_MMA(1, 0, At, B0); PG8_MMA(1, 1, At, B1); PG8_BAR; PG8_SCHED;
;             PG8_LDB(B0, 1, 0); PG8_LDB(B1, 1, 1); PG8_SCHED; PG8_LDA(At, 1, 0); PG8_STAGE(PG8_SA(0, 1), a2 + hstep, voffA);
;             PG8_WAIT_V(8); PG8_WAIT_L(0); PG8_BAR; PG8_MMA(0, 0, At, B0); PG8_MMA(0, 1, At, B1); PG8_BAR; PG8_SCHED;
	s_setprio 0
	s_waitcnt lgkmcnt(0)
	v_mfma_f32_16x16x32_bf16 v[66:69], v[134:137], v[216:219], v[66:69]
	v_mfma_f32_16x16x32_bf16 v[62:65], v[154:157], v[216:219], v[62:65]
	v_mfma_f32_16x16x32_bf16 v[58:61], v[134:137], v[224:227], v[58:61]
	v_mfma_f32_16x16x32_bf16 v[54:57], v[154:157], v[224:227], v[54:57]
	v_mfma_f32_16x16x32_bf16 v[50:53], v[134:137], v[232:235], v[50:53]
	v_mfma_f32_16x16x32_bf16 v[46:49], v[154:157], v[232:235], v[46:49]
	v_mfma_f32_16x16x32_bf16 v[42:45], v[134:137], v[240:243], v[42:45]
	v_mfma_f32_16x16x32_bf16 v[38:41], v[154:157], v[240:243], v[38:41]
	v_mfma_f32_16x16x32_bf16 v[66:69], v[138:141], v[220:223], v[66:69]
	v_mfma_f32_16x16x32_bf16 v[62:65], v[158:161], v[220:223], v[62:65]
	v_mfma_f32_16x16x32_bf16 v[58:61], v[138:141], v[228:231], v[58:61]
	v_mfma_f32_16x16x32_bf16 v[54:57], v[158:161], v[228:231], v[54:57]
	v_mfma_f32_16x16x32_bf16 v[50:53], v[138:141], v[236:239], v[50:53]
	v_mfma_f32_16x16x32_bf16 v[46:49], v[158:161], v[236:239], v[46:49]
	v_mfma_f32_16x16x32_bf16 v[42:45], v[138:141], v[244:247], v[42:45]
	v_mfma_f32_16x16x32_bf16 v[38:41], v[158:161], v[244:247], v[38:41]
	v_mfma_f32_16x16x32_bf16 v[34:37], v[178:181], v[216:219], v[34:37]
	ds_read_b128 v[134:137], v175 offset:32768
	v_mfma_f32_16x16x32_bf16 v[30:33], v[208:211], v[216:219], v[30:33]
	ds_read_b128 v[138:141], v175 offset:33792
	v_mfma_f32_16x16x32_bf16 v[26:29], v[178:181], v[224:227], v[26:29]
	ds_read_b128 v[154:157], v175 offset:34816
	v_mfma_f32_16x16x32_bf16 v[22:25], v[208:211], v[224:227], v[22:25]
	ds_read_b128 v[158:161], v175 offset:35840
	v_mfma_f32_16x16x32_bf16 v[18:21], v[178:181], v[232:235], v[18:21]
	v_mfma_f32_16x16x32_bf16 v[14:17], v[208:211], v[232:235], v[14:17]
	v_mfma_f32_16x16x32_bf16 v[10:13], v[178:181], v[240:243], v[10:13]
	v_mfma_f32_16x16x32_bf16 v[4:7], v[208:211], v[240:243], v[6:9]
	v_mfma_f32_16x16x32_bf16 v[34:37], v[204:207], v[220:223], v[34:37]
	v_mfma_f32_16x16x32_bf16 v[30:33], v[212:215], v[220:223], v[30:33]
	v_mfma_f32_16x16x32_bf16 v[26:29], v[204:207], v[228:231], v[26:29]
	v_mfma_f32_16x16x32_bf16 v[22:25], v[212:215], v[228:231], v[22:25]
	v_mfma_f32_16x16x32_bf16 v[18:21], v[204:207], v[236:239], v[18:21]
	v_mfma_f32_16x16x32_bf16 v[14:17], v[212:215], v[236:239], v[14:17]
	v_mfma_f32_16x16x32_bf16 v[10:13], v[204:207], v[244:247], v[10:13]
	v_mfma_f32_16x16x32_bf16 v[4:7], v[212:215], v[244:247], v[4:7]
	s_setprio 3
	s_barrier
	s_add_i32 s27, 0, 0x18000
	s_add_i32 s29, 0, 0x1c000
	ds_read_b128 v[178:181], v175 offset:49152
	ds_read_b128 v[204:207], v175 offset:50176
	ds_read_b128 v[208:211], v175 offset:51200
	ds_read_b128 v[212:215], v175 offset:52224
	s_add_u32 s100, s44, 0x80
	s_addc_u32 s101, s45, 0
	s_add_u32 s44, s44, 0x40000
	s_addc_u32 s45, s45, 0
	s_mov_b32 m0, s57
	ds_read_b128 v[216:219], v177 offset:32768
	ds_read_b128 v[220:223], v177 offset:33792
	ds_read_b128 v[224:227], v177 offset:34816
	ds_read_b128 v[228:231], v177 offset:35840
	ds_read_b128 v[232:235], v177 offset:36864
	ds_read_b128 v[236:239], v177 offset:37888
	ds_read_b128 v[240:243], v177 offset:38912
	ds_read_b128 v[244:247], v177 offset:39936
	global_load_lds_dwordx4 v142, s[44:45]
	s_mov_b32 m0, s58
	s_nop 0
	global_load_lds_dwordx4 v146, s[44:45]
	s_nop 0
	s_waitcnt vmcnt(8) lgkmcnt(0)
	s_barrier
	s_setprio 0
	s_waitcnt lgkmcnt(0)
	v_mfma_f32_16x16x32_bf16 v[130:133], v[134:137], v[216:219], v[130:133]
	v_mfma_f32_16x16x32_bf16 v[126:129], v[154:157], v[216:219], v[126:129]
	v_mfma_f32_16x16x32_bf16 v[122:125], v[134:137], v[224:227], v[122:125]
	v_mfma_f32_16x16x32_bf16 v[118:121], v[154:157], v[224:227], v[118:121]
	v_mfma_f32_16x16x32_bf16 v[114:117], v[134:137], v[232:235], v[114:117]
	v_mfma_f32_16x16x32_bf16 v[110:113], v[154:157], v[232:235], v[110:113]
	v_mfma_f32_16x16x32_bf16 v[106:109], v[134:137], v[240:243], v[106:109]
	v_mfma_f32_16x16x32_bf16 v[102:105], v[154:157], v[240:243], v[102:105]
	v_mfma_f32_16x16x32_bf16 v[130:133], v[138:141], v[220:223], v[130:133]
	v_mfma_f32_16x16x32_bf16 v[126:129], v[158:161], v[220:223], v[126:129]
	v_mfma_f32_16x16x32_bf16 v[122:125], v[138:141], v[228:231], v[122:125]
	v_mfma_f32_16x16x32_bf16 v[118:121], v[158:161], v[228:231], v[118:121]
	v_mfma_f32_16x16x32_bf16 v[114:117], v[138:141], v[236:239], v[114:117]
	v_mfma_f32_16x16x32_bf16 v[110:113], v[158:161], v[236:239], v[110:113]
	v_mfma_f32_16x16x32_bf16 v[106:109], v[138:141], v[244:247], v[106:109]
	v_mfma_f32_16x16x32_bf16 v[102:105], v[158:161], v[244:247], v[102:105]
	v_mfma_f32_16x16x32_bf16 v[98:101], v[178:181], v[216:219], v[98:101]
	v_mfma_f32_16x16x32_bf16 v[94:97], v[208:211], v[216:219], v[94:97]
	v_mfma_f32_16x16x32_bf16 v[90:93], v[178:181], v[224:227], v[90:93]
	v_mfma_f32_16x16x32_bf16 v[86:89], v[208:211], v[224:227], v[86:89]
	v_mfma_f32_16x16x32_bf16 v[82:85], v[178:181], v[232:235], v[82:85]
	v_mfma_f32_16x16x32_bf16 v[78:81], v[208:211], v[232:235], v[78:81]
	v_mfma_f32_16x16x32_bf16 v[74:77], v[178:181], v[240:243], v[74:77]
	v_mfma_f32_16x16x32_bf16 v[70:73], v[208:211], v[240:243], v[70:73]
	v_mfma_f32_16x16x32_bf16 v[98:101], v[204:207], v[220:223], v[98:101]
	v_mfma_f32_16x16x32_bf16 v[94:97], v[212:215], v[220:223], v[94:97]
	v_mfma_f32_16x16x32_bf16 v[90:93], v[204:207], v[228:231], v[90:93]
	v_mfma_f32_16x16x32_bf16 v[86:89], v[212:215], v[228:231], v[86:89]
	v_mfma_f32_16x16x32_bf16 v[82:85], v[204:207], v[236:239], v[82:85]
	v_mfma_f32_16x16x32_bf16 v[78:81], v[212:215], v[236:239], v[78:81]
	v_mfma_f32_16x16x32_bf16 v[74:77], v[204:207], v[244:247], v[74:77]
	v_mfma_f32_16x16x32_bf16 v[70:73], v[212:215], v[244:247], v[70:73]
	s_setprio 3
	s_barrier
; #define PG8_STAGE(bufoff, gbase, voff) do { _Pragma("unroll") for (int _i = 0; _i < 2; ++_i) \
;         __builtin_amdgcn_global_load_lds((const unsigned*)((const char*)(gbase) + (voff)[_i]), (PG8_LAS unsigned*)(lds + (bufoff) + ldsw + _i * 8192), 16, 0, 0); } while (0)
; #define PG8_LDA(dst, b, h) do { _Pragma("unroll") for (int m = 0; m < 4; ++m) _Pragma("unroll") for (int k = 0; k < 2; ++k) dst[m][k] = *(const PG8_LAS bf16x8*)(lds + PG8_SA(b, h) + aoff + m * 2048 + k * 1024); } while (0)
; #define PG8_MMA(ai, bj, At, Bt) do { __builtin_amdgcn_s_setprio(1); _Pragma("unroll") for (int m = 0; m < 4; ++m) _Pragma("unroll") for (int n = 0; n < 2; ++n) _Pragma("unroll") for (int k = 0; k < 2; ++k) \
;         acc[ai][bj][m][n] = __builtin_amdgcn_mfma_f32_16x16x32_bf16(Bt[n][k], At[m][k], acc[ai][bj][m][n], 0, 0, 0); __builtin_amdgcn_s_setprio(0); } while (0)
; #define PG8_WAIT_V(n) asm volatile("s_waitcnt vmcnt(" #n ")" ::: "memory")
; #define PG8_WAIT_L(n) asm volatile("s_waitcnt lgkmcnt(" #n ")" ::: "memory")
; #define PG8_BAR __builtin_amdgcn_s_barrier()
; #define PG8_SCHED __builtin_amdgcn_sched_barrier(0)
; template <class Epi, class Sched, bool ALIGN_EPI = false, bool SP2 = false>
; __device__ __forceinline__ void gemm_phase(PG8_LAS unsigned char* lds, const Gemm g, const Sched& S, const Epi& E) {
;     ...
;             PG8_LDA(At, 1, 1); PG8_STAGE(PG8_SB(1, 0), b3, voffB); PG8_STAGE(PG8_SB(1, 1), b3 + hstep, voffB); PG8_STAGE(PG8_SA(1, 0), a3, voffA);
;             PG8_WAIT_V(8); PG8_WAIT_L(0); PG8_BAR; PG8_MMA(1, 0, At, B0); PG8_MMA(1, 1, At, B1); PG8_BAR; PG8_SCHED;
	s_add_i32 s27, s27, s54
	s_add_i32 m0, s27, 0xffffff80
	ds_read_b128 v[216:219], v177 offset:49152
	ds_read_b128 v[220:223], v177 offset:50176
	ds_read_b128 v[224:227], v177 offset:51200
	ds_read_b128 v[228:231], v177 offset:52224
	ds_read_b128 v[232:235], v177 offset:53248
	ds_read_b128 v[236:239], v177 offset:54272
	ds_read_b128 v[240:243], v177 offset:55296
	ds_read_b128 v[244:247], v177 offset:56320
	global_load_lds_dwordx4 v144, s[42:43] offset:128
	s_add_i32 m0, s27, 0x1f80
	s_add_i32 s27, s29, s54
	global_load_lds_dwordx4 v148, s[42:43] offset:128
	s_add_u32 s42, s42, 0x40080
	s_addc_u32 s43, s43, 0
	s_mov_b32 m0, s27
	s_nop 0
	global_load_lds_dwordx4 v144, s[42:43]
	s_add_i32 m0, s27, 0x2000
	s_nop 0
	global_load_lds_dwordx4 v148, s[42:43]
	s_mov_b32 m0, s61
	s_nop 0
	global_load_lds_dwordx4 v142, s[100:101]
	s_mov_b32 m0, s62
	s_nop 0
	global_load_lds_dwordx4 v146, s[100:101]
	s_waitcnt vmcnt(8) lgkmcnt(0)
	s_barrier
	s_setprio 0
	s_waitcnt lgkmcnt(0)
	v_mfma_f32_16x16x32_bf16 v[66:69], v[134:137], v[216:219], v[66:69]
	v_mfma_f32_16x16x32_bf16 v[62:65], v[154:157], v[216:219], v[62:65]
	v_mfma_f32_16x16x32_bf16 v[58:61], v[134:137], v[224:227], v[58:61]
	v_mfma_f32_16x16x32_bf16 v[54:57], v[154:157], v[224:227], v[54:57]
	v_mfma_f32_16x16x32_bf16 v[50:53], v[134:137], v[232:235], v[50:53]
	v_mfma_f32_16x16x32_bf16 v[46:49], v[154:157], v[232:235], v[46:49]
	v_mfma_f32_16x16x32_bf16 v[42:45], v[134:137], v[240:243], v[42:45]
	v_mfma_f32_16x16x32_bf16 v[38:41], v[154:157], v[240:243], v[38:41]
	v_mfma_f32_16x16x32_bf16 v[66:69], v[138:141], v[220:223], v[66:69]
	v_mfma_f32_16x16x32_bf16 v[62:65], v[158:161], v[220:223], v[62:65]
	v_mfma_f32_16x16x32_bf16 v[58:61], v[138:141], v[228:231], v[58:61]
	v_mfma_f32_16x16x32_bf16 v[54:57], v[158:161], v[228:231], v[54:57]
	v_mfma_f32_16x16x32_bf16 v[50:53], v[138:141], v[236:239], v[50:53]
	v_mfma_f32_16x16x32_bf16 v[46:49], v[158:161], v[236:239], v[46:49]
	v_mfma_f32_16x16x32_bf16 v[42:45], v[138:141], v[244:247], v[42:45]
	v_mfma_f32_16x16x32_bf16 v[38:41], v[158:161], v[244:247], v[38:41]
	v_mfma_f32_16x16x32_bf16 v[34:37], v[178:181], v[216:219], v[34:37]
	ds_read_b128 v[134:137], v175
	v_mfma_f32_16x16x32_bf16 v[30:33], v[208:211], v[216:219], v[30:33]
	ds_read_b128 v[138:141], v175 offset:1024
	v_mfma_f32_16x16x32_bf16 v[26:29], v[178:181], v[224:227], v[26:29]
	ds_read_b128 v[154:157], v175 offset:2048
	v_mfma_f32_16x16x32_bf16 v[22:25], v[208:211], v[224:227], v[22:25]
	ds_read_b128 v[158:161], v175 offset:3072
	v_mfma_f32_16x16x32_bf16 v[18:21], v[178:181], v[232:235], v[18:21]
	v_mfma_f32_16x16x32_bf16 v[14:17], v[208:211], v[232:235], v[14:17]
	v_mfma_f32_16x16x32_bf16 v[8:11], v[178:181], v[240:243], v[10:13]
	v_mfma_f32_16x16x32_bf16 v[4:7], v[208:211], v[240:243], v[4:7]
	v_mfma_f32_16x16x32_bf16 v[34:37], v[204:207], v[220:223], v[34:37]
	v_mfma_f32_16x16x32_bf16 v[30:33], v[212:215], v[220:223], v[30:33]
	v_mfma_f32_16x16x32_bf16 v[26:29], v[204:207], v[228:231], v[26:29]
	v_mfma_f32_16x16x32_bf16 v[22:25], v[212:215], v[228:231], v[22:25]
	v_mfma_f32_16x16x32_bf16 v[18:21], v[204:207], v[236:239], v[18:21]
	v_mfma_f32_16x16x32_bf16 v[14:17], v[212:215], v[236:239], v[14:17]
	v_mfma_f32_16x16x32_bf16 v[10:13], v[204:207], v[244:247], v[8:11]
	v_mfma_f32_16x16x32_bf16 v[6:9], v[212:215], v[244:247], v[4:7]
	s_setprio 3
	s_barrier
	s_add_i32 s26, s26, 2
	s_add_u32 s40, s40, 0x100
	s_addc_u32 s41, s41, 0
	s_add_u32 s11, s11, 0x100
	s_addc_u32 s13, s13, 0
	s_cmp_gt_u32 s26, 13
	s_cbranch_scc0 .LBB0_2096
	s_and_b64 vcc, exec, s[8:9]
	s_cbranch_vccz .LBB0_2099
	s_barrier

; #define PG8_STAGE(bufoff, gbase, voff) do { _Pragma("unroll") for (int _i = 0; _i < 2; ++_i) \
;         __builtin_amdgcn_global_load_lds((const unsigned*)((const char*)(gbase) + (voff)[_i]), (PG8_LAS unsigned*)(lds + (bufoff) + ldsw + _i * 8192), 16, 0, 0); } while (0)
; #define PG8_LDA(dst, b, h) do { _Pragma("unroll") for (int m = 0; m < 4; ++m) _Pragma("unroll") for (int k = 0; k < 2; ++k) dst[m][k] = *(const PG8_LAS bf16x8*)(lds + PG8_SA(b, h) + aoff + m * 2048 + k * 1024); } while (0)
; #define PG8_LDB(dst, b, h) do { _Pragma("unroll") for (int n = 0; n < 2; ++n) _Pragma("unroll") for (int k = 0; k < 2; ++k) dst[n][k] = *(const PG8_LAS bf16x8*)(lds + PG8_SB(b, h) + boff + n * 2048 + k * 1024); } while (0)
; #define PG8_MMA(ai, bj, At, Bt) do { __builtin_amdgcn_s_setprio(1); _Pragma("unroll") for (int m = 0; m < 4; ++m) _Pragma("unroll") for (int n = 0; n < 2; ++n) _Pragma("unroll") for (int k = 0; k < 2; ++k) \
;         acc[ai][bj][m][n] = __builtin_amdgcn_mfma_f32_16x16x32_bf16(Bt[n][k], At[m][k], acc[ai][bj][m][n], 0, 0, 0); __builtin_amdgcn_s_setprio(0); } while (0)
; #define PG8_WAIT_V(n) asm volatile("s_waitcnt vmcnt(" #n ")" ::: "memory")
; template <class Epi, class Sched, bool ALIGN_EPI = false, bool SP2 = false>
; __device__ __forceinline__ void gemm_phase(PG8_LAS unsigned char* lds, const Gemm g, const Sched& S, const Epi& E) {
;     ...
;         for (int t = 0; t < nt; t += 2) {
;             const bool last = (t == nt - 2);
;             const char* a1 = cA + (size_t)(t + 1) * kstep;
;             const char* a2 = last ? nA : cA + (size_t)(t + 2) * kstep; const char* b2 = last ? nB : cB + (size_t)(t + 2) * kstep;
;             const char* a3 = a2 + kstep; const char* b3 = b2 + kstep;
;             if (last && has_next) S.a_ready(nxt);
;             if constexpr (SP2) {
;             PG8_LDB(B0, 0, 0); PG8_LDB(B1, 0, 1); PG8_SCHED; PG8_LDA(At, 0, 0); PG8_STAGE(PG8_SA(1, 1), a1 + hstep, voffA);
;             PG8_WAIT_V(8); PG8_WAIT_L(0); PG8_BAR; PG8_MMA(0, 0, At, B0); PG8_MMA(0, 1, At, B1); PG8_BAR; PG8_SCHED;
;     ...
;         if (zero_acc) {
; #pragma unroll
;         for (int a = 0; a < 2; ++a)
; #pragma unroll
;             for (int b = 0; b < 2; ++b)
; #pragma unroll
;                 for (int m = 0; m < 4; ++m)
; #pragma unroll
;                     for (int n = 0; n < 2; ++n) acc[a][b][m][n] = (f32x4){0.f, 0.f, 0.f, 0.f};
.LBB0_2184:
	s_add_u32 s2, s42, 0x100
	v_mov_b32_e32 v4, 0
	s_addc_u32 s29, s43, 0
	s_mov_b32 s31, -2
	s_waitcnt lgkmcnt(0)
	v_mov_b32_e32 v5, v4
	v_mov_b32_e32 v6, v4
	v_mov_b32_e32 v7, v4
	v_mov_b32_e32 v8, v4
	v_mov_b32_e32 v9, v4
	v_mov_b32_e32 v10, v4
	v_mov_b32_e32 v11, v4
	v_mov_b32_e32 v20, v4
	v_mov_b32_e32 v21, v4
	v_mov_b32_e32 v22, v4
	v_mov_b32_e32 v23, v4
	v_mov_b32_e32 v24, v4
	v_mov_b32_e32 v25, v4
	v_mov_b32_e32 v26, v4
	v_mov_b32_e32 v27, v4
	v_mov_b32_e32 v36, v4
	v_mov_b32_e32 v37, v4
	v_mov_b32_e32 v38, v4
	v_mov_b32_e32 v39, v4
	v_mov_b32_e32 v40, v4
	v_mov_b32_e32 v41, v4
	v_mov_b32_e32 v42, v4
	v_mov_b32_e32 v43, v4
	v_mov_b32_e32 v52, v4
	v_mov_b32_e32 v53, v4
	v_mov_b32_e32 v54, v4
	v_mov_b32_e32 v55, v4
	v_mov_b32_e32 v56, v4
	v_mov_b32_e32 v57, v4
	v_mov_b32_e32 v58, v4
	v_mov_b32_e32 v59, v4
	v_mov_b32_e32 v12, v4
	v_mov_b32_e32 v13, v4
	v_mov_b32_e32 v14, v4
	v_mov_b32_e32 v15, v4
	v_mov_b32_e32 v16, v4
	v_mov_b32_e32 v17, v4
	v_mov_b32_e32 v18, v4
	v_mov_b32_e32 v19, v4
	v_mov_b32_e32 v28, v4
	v_mov_b32_e32 v29, v4
	v_mov_b32_e32 v30, v4
	v_mov_b32_e32 v31, v4
	v_mov_b32_e32 v32, v4
	v_mov_b32_e32 v33, v4
	v_mov_b32_e32 v34, v4
	v_mov_b32_e32 v35, v4
	v_mov_b32_e32 v44, v4
	v_mov_b32_e32 v45, v4
	v_mov_b32_e32 v46, v4
	v_mov_b32_e32 v47, v4
	v_mov_b32_e32 v48, v4
	v_mov_b32_e32 v49, v4
	v_mov_b32_e32 v50, v4
	v_mov_b32_e32 v51, v4
	v_mov_b32_e32 v60, v4
	v_mov_b32_e32 v61, v4
	v_mov_b32_e32 v62, v4
	v_mov_b32_e32 v63, v4
	v_mov_b32_e32 v64, v4
	v_mov_b32_e32 v65, v4
	v_mov_b32_e32 v66, v4
	v_mov_b32_e32 v67, v4
	v_mov_b32_e32 v68, v4
	v_mov_b32_e32 v69, v4
	v_mov_b32_e32 v70, v4
	v_mov_b32_e32 v71, v4
	v_mov_b32_e32 v72, v4
	v_mov_b32_e32 v73, v4
	v_mov_b32_e32 v74, v4
	v_mov_b32_e32 v75, v4
	v_mov_b32_e32 v84, v4
	v_mov_b32_e32 v85, v4
	v_mov_b32_e32 v86, v4
	v_mov_b32_e32 v87, v4
	v_mov_b32_e32 v88, v4
	v_mov_b32_e32 v89, v4
	v_mov_b32_e32 v90, v4
	v_mov_b32_e32 v91, v4
	v_mov_b32_e32 v100, v4
	v_mov_b32_e32 v101, v4
	v_mov_b32_e32 v102, v4
	v_mov_b32_e32 v103, v4
	v_mov_b32_e32 v104, v4
	v_mov_b32_e32 v105, v4
	v_mov_b32_e32 v106, v4
	v_mov_b32_e32 v107, v4
	v_mov_b32_e32 v116, v4
	v_mov_b32_e32 v117, v4
	v_mov_b32_e32 v118, v4
	v_mov_b32_e32 v119, v4
	v_mov_b32_e32 v120, v4
	v_mov_b32_e32 v121, v4
	v_mov_b32_e32 v122, v4
	v_mov_b32_e32 v123, v4
	v_mov_b32_e32 v76, v4
	v_mov_b32_e32 v77, v4
	v_mov_b32_e32 v78, v4
	v_mov_b32_e32 v79, v4
	v_mov_b32_e32 v80, v4
	v_mov_b32_e32 v81, v4
	v_mov_b32_e32 v82, v4
	v_mov_b32_e32 v83, v4
	v_mov_b32_e32 v92, v4
	v_mov_b32_e32 v93, v4
	v_mov_b32_e32 v94, v4
	v_mov_b32_e32 v95, v4
	v_mov_b32_e32 v96, v4
	v_mov_b32_e32 v97, v4
	v_mov_b32_e32 v98, v4
	v_mov_b32_e32 v99, v4
	v_mov_b32_e32 v108, v4
	v_mov_b32_e32 v109, v4
	v_mov_b32_e32 v110, v4
	v_mov_b32_e32 v111, v4
	v_mov_b32_e32 v112, v4
	v_mov_b32_e32 v113, v4
	v_mov_b32_e32 v114, v4
	v_mov_b32_e32 v115, v4
	v_mov_b32_e32 v124, v4
	v_mov_b32_e32 v125, v4
	v_mov_b32_e32 v126, v4
	v_mov_b32_e32 v127, v4
	v_mov_b32_e32 v128, v4
	v_mov_b32_e32 v129, v4
	v_mov_b32_e32 v130, v4
	v_mov_b32_e32 v131, v4
	v_add_u32_e32 v243, 0x10000, v173
	ds_read_b128 v[142:145], v243
	ds_read_b128 v[146:149], v243 offset:1024
	ds_read_b128 v[150:153], v243 offset:2048
	ds_read_b128 v[154:157], v243 offset:3072
	.p2align 6
	s_nop 0
.LBB0_2185:
	s_add_u32 s42, s40, 0x100
	s_addc_u32 s43, s41, 0
	s_add_i32 s37, 0, 0x10000
	s_cmp_eq_u32 s31, 28
	s_cselect_b32 s47, s5, s43
	s_cselect_b32 s46, s4, s42
	s_cselect_b32 s45, s35, s29
	s_cselect_b32 s44, s34, s2
	s_add_i32 s39, 0, 0x14000
	ds_read_b128 v[158:161], v243 offset:16384
	ds_read_b128 v[174:177], v243 offset:17408
	ds_read_b128 v[180:183], v243 offset:18432
	ds_read_b128 v[204:207], v243 offset:19456
	v_lshl_add_u64 v[162:163], s[40:41], 0, v[138:139]
	s_add_i32 m0, s55, 0xc000
	ds_read_b128 v[208:211], v179
	ds_read_b128 v[212:215], v179 offset:1024
	ds_read_b128 v[216:219], v179 offset:2048
	ds_read_b128 v[220:223], v179 offset:3072
	ds_read_b128 v[224:227], v179 offset:4096
	ds_read_b128 v[228:231], v179 offset:5120
	ds_read_b128 v[232:235], v179 offset:6144
	ds_read_b128 v[236:239], v179 offset:7168
	global_load_lds_dwordx4 v[162:163], off
	v_lshl_add_u64 v[162:163], s[40:41], 0, v[140:141]
	s_add_i32 m0, s55, 0xe000
	s_nop 0
	global_load_lds_dwordx4 v[162:163], off
	s_nop 0
	s_waitcnt vmcnt(8) lgkmcnt(0)
	s_barrier
	s_setprio 0
	s_waitcnt lgkmcnt(0)
	v_mfma_f32_16x16x32_bf16 v[128:131], v[142:145], v[208:211], v[128:131]
	v_mfma_f32_16x16x32_bf16 v[124:127], v[150:153], v[208:211], v[124:127]
	v_mfma_f32_16x16x32_bf16 v[112:115], v[142:145], v[216:219], v[112:115]
	v_mfma_f32_16x16x32_bf16 v[108:111], v[150:153], v[216:219], v[108:111]
	v_mfma_f32_16x16x32_bf16 v[96:99], v[142:145], v[224:227], v[96:99]
	v_mfma_f32_16x16x32_bf16 v[92:95], v[150:153], v[224:227], v[92:95]
	v_mfma_f32_16x16x32_bf16 v[80:83], v[142:145], v[232:235], v[80:83]
	v_mfma_f32_16x16x32_bf16 v[76:79], v[150:153], v[232:235], v[76:79]
	v_mfma_f32_16x16x32_bf16 v[128:131], v[146:149], v[212:215], v[128:131]
	v_mfma_f32_16x16x32_bf16 v[124:127], v[154:157], v[212:215], v[124:127]
	v_mfma_f32_16x16x32_bf16 v[112:115], v[146:149], v[220:223], v[112:115]
	v_mfma_f32_16x16x32_bf16 v[108:111], v[154:157], v[220:223], v[108:111]
	v_mfma_f32_16x16x32_bf16 v[96:99], v[146:149], v[228:231], v[96:99]
	v_mfma_f32_16x16x32_bf16 v[92:95], v[154:157], v[228:231], v[92:95]
	v_mfma_f32_16x16x32_bf16 v[80:83], v[146:149], v[236:239], v[80:83]
	v_mfma_f32_16x16x32_bf16 v[76:79], v[154:157], v[236:239], v[76:79]
	v_mfma_f32_16x16x32_bf16 v[120:123], v[158:161], v[208:211], v[120:123]
	v_mfma_f32_16x16x32_bf16 v[116:119], v[180:183], v[208:211], v[116:119]
	v_mfma_f32_16x16x32_bf16 v[104:107], v[158:161], v[216:219], v[104:107]
	v_mfma_f32_16x16x32_bf16 v[100:103], v[180:183], v[216:219], v[100:103]
	v_mfma_f32_16x16x32_bf16 v[88:91], v[158:161], v[224:227], v[88:91]
	v_mfma_f32_16x16x32_bf16 v[84:87], v[180:183], v[224:227], v[84:87]
	v_mfma_f32_16x16x32_bf16 v[72:75], v[158:161], v[232:235], v[72:75]
	v_mfma_f32_16x16x32_bf16 v[68:71], v[180:183], v[232:235], v[68:71]
	v_mfma_f32_16x16x32_bf16 v[120:123], v[174:177], v[212:215], v[120:123]
	v_mfma_f32_16x16x32_bf16 v[116:119], v[204:207], v[212:215], v[116:119]
	v_mfma_f32_16x16x32_bf16 v[104:107], v[174:177], v[220:223], v[104:107]
	v_mfma_f32_16x16x32_bf16 v[100:103], v[204:207], v[220:223], v[100:103]
	v_mfma_f32_16x16x32_bf16 v[88:91], v[174:177], v[228:231], v[88:91]
	v_mfma_f32_16x16x32_bf16 v[84:87], v[204:207], v[228:231], v[84:87]
	v_mfma_f32_16x16x32_bf16 v[72:75], v[174:177], v[236:239], v[72:75]
	v_mfma_f32_16x16x32_bf16 v[68:71], v[204:207], v[236:239], v[68:71]
	s_setprio 3
	s_barrier
; #define PG8_STAGE(bufoff, gbase, voff) do { _Pragma("unroll") for (int _i = 0; _i < 2; ++_i) \
;         __builtin_amdgcn_global_load_lds((const unsigned*)((const char*)(gbase) + (voff)[_i]), (PG8_LAS unsigned*)(lds + (bufoff) + ldsw + _i * 8192), 16, 0, 0); } while (0)
; #define PG8_LDA(dst, b, h) do { _Pragma("unroll") for (int m = 0; m < 4; ++m) _Pragma("unroll") for (int k = 0; k < 2; ++k) dst[m][k] = *(const PG8_LAS bf16x8*)(lds + PG8_SA(b, h) + aoff + m * 2048 + k * 1024); } while (0)
; #define PG8_LDB(dst, b, h) do { _Pragma("unroll") for (int n = 0; n < 2; ++n) _Pragma("unroll") for (int k = 0; k < 2; ++k) dst[n][k] = *(const PG8_LAS bf16x8*)(lds + PG8_SB(b, h) + boff + n * 2048 + k * 1024); } while (0)
; #define PG8_MMA(ai, bj, At, Bt) do { __builtin_amdgcn_s_setprio(1); _Pragma("unroll") for (int m = 0; m < 4; ++m) _Pragma("unroll") for (int n = 0; n < 2; ++n) _Pragma("unroll") for (int k = 0; k < 2; ++k) \
;         acc[ai][bj][m][n] = __builtin_amdgcn_mfma_f32_16x16x32_bf16(Bt[n][k], At[m][k], acc[ai][bj][m][n], 0, 0, 0); __builtin_amdgcn_s_setprio(0); } while (0)
; #define PG8_WAIT_V(n) asm volatile("s_waitcnt vmcnt(" #n ")" ::: "memory")
; #define PG8_WAIT_L(n) asm volatile("s_waitcnt lgkmcnt(" #n ")" ::: "memory")
; #define PG8_BAR __builtin_amdgcn_s_barrier()
; #define PG8_SCHED __builtin_amdgcn_sched_barrier(0)
; template <class Epi, class Sched, bool ALIGN_EPI = false, bool SP2 = false>
; __device__ __forceinline__ void gemm_phase(PG8_LAS unsigned char* lds, const Gemm g, const Sched& S, const Epi& E) {
;     ...
;             PG8_LDA(At, 0, 1); PG8_STAGE(PG8_SB(0, 0), b2, voffB); PG8_STAGE(PG8_SB(0, 1), b2 + hstep, voffB); PG8_STAGE(PG8_SA(0, 0), a2, voffA);
;             PG8_WAIT_V(8); PG8_WAIT_L(0); PG8_BAR; PG8_MMA(1, 0, At, B0); PG8_MMA(1, 1, At, B1); PG8_BAR; PG8_SCHED;
;             PG8_LDB(B0, 1, 0); PG8_LDB(B1, 1, 1); PG8_SCHED; PG8_LDA(At, 1, 0); PG8_STAGE(PG8_SA(0, 1), a2 + hstep, voffA);
;             PG8_WAIT_V(8); PG8_WAIT_L(0); PG8_BAR; PG8_MMA(0, 0, At, B0); PG8_MMA(0, 1, At, B1); PG8_BAR; PG8_SCHED;
	s_add_i32 s37, s37, s54
	s_mov_b32 m0, s37
	ds_read_b128 v[208:211], v179 offset:16384
	ds_read_b128 v[212:215], v179 offset:17408
	ds_read_b128 v[216:219], v179 offset:18432
	ds_read_b128 v[220:223], v179 offset:19456
	ds_read_b128 v[224:227], v179 offset:20480
	ds_read_b128 v[228:231], v179 offset:21504
	ds_read_b128 v[232:235], v179 offset:22528
	ds_read_b128 v[236:239], v179 offset:23552
	global_load_lds_dwordx4 v2, s[44:45]
	s_add_i32 m0, s37, 0x2000
	s_add_u32 s40, s44, 0x80000
	s_addc_u32 s41, s45, 0
	s_add_i32 s37, s39, s54
	global_load_lds_dwordx4 v132, s[44:45]
	s_mov_b32 m0, s37
	s_nop 0
	global_load_lds_dwordx4 v2, s[40:41]
	s_add_i32 m0, s37, 0x2000
	s_nop 0
	global_load_lds_dwordx4 v132, s[40:41]
	s_mov_b32 m0, s55
	s_nop 0
	global_load_lds_dwordx4 v2, s[46:47]
	s_mov_b32 m0, s56
	s_nop 0
	global_load_lds_dwordx4 v132, s[46:47]
	s_nop 0
	s_waitcnt vmcnt(8) lgkmcnt(0)
	s_barrier
	s_setprio 0
	s_waitcnt lgkmcnt(0)
	v_mfma_f32_16x16x32_bf16 v[64:67], v[142:145], v[208:211], v[64:67]
	v_mfma_f32_16x16x32_bf16 v[60:63], v[150:153], v[208:211], v[60:63]
	v_mfma_f32_16x16x32_bf16 v[48:51], v[142:145], v[216:219], v[48:51]
	v_mfma_f32_16x16x32_bf16 v[44:47], v[150:153], v[216:219], v[44:47]
	v_mfma_f32_16x16x32_bf16 v[32:35], v[142:145], v[224:227], v[32:35]
	v_mfma_f32_16x16x32_bf16 v[28:31], v[150:153], v[224:227], v[28:31]
	v_mfma_f32_16x16x32_bf16 v[16:19], v[142:145], v[232:235], v[16:19]
	v_mfma_f32_16x16x32_bf16 v[12:15], v[150:153], v[232:235], v[12:15]
	v_mfma_f32_16x16x32_bf16 v[64:67], v[146:149], v[212:215], v[64:67]
	v_mfma_f32_16x16x32_bf16 v[60:63], v[154:157], v[212:215], v[60:63]
	v_mfma_f32_16x16x32_bf16 v[48:51], v[146:149], v[220:223], v[48:51]
	v_mfma_f32_16x16x32_bf16 v[44:47], v[154:157], v[220:223], v[44:47]
	v_mfma_f32_16x16x32_bf16 v[32:35], v[146:149], v[228:231], v[32:35]
	v_mfma_f32_16x16x32_bf16 v[28:31], v[154:157], v[228:231], v[28:31]
	v_mfma_f32_16x16x32_bf16 v[16:19], v[146:149], v[236:239], v[16:19]
	v_mfma_f32_16x16x32_bf16 v[12:15], v[154:157], v[236:239], v[12:15]
	v_mfma_f32_16x16x32_bf16 v[56:59], v[158:161], v[208:211], v[56:59]
	ds_read_b128 v[142:145], v243 offset:32768
	v_mfma_f32_16x16x32_bf16 v[52:55], v[180:183], v[208:211], v[52:55]
	ds_read_b128 v[146:149], v243 offset:33792
	v_mfma_f32_16x16x32_bf16 v[40:43], v[158:161], v[216:219], v[40:43]
	ds_read_b128 v[150:153], v243 offset:34816
	v_mfma_f32_16x16x32_bf16 v[36:39], v[180:183], v[216:219], v[36:39]
	ds_read_b128 v[154:157], v243 offset:35840
	v_mfma_f32_16x16x32_bf16 v[24:27], v[158:161], v[224:227], v[24:27]
	v_mfma_f32_16x16x32_bf16 v[20:23], v[180:183], v[224:227], v[20:23]
	v_mfma_f32_16x16x32_bf16 v[8:11], v[158:161], v[232:235], v[8:11]
	v_mfma_f32_16x16x32_bf16 v[4:7], v[180:183], v[232:235], v[4:7]
	v_mfma_f32_16x16x32_bf16 v[56:59], v[174:177], v[212:215], v[56:59]
	v_mfma_f32_16x16x32_bf16 v[52:55], v[204:207], v[212:215], v[52:55]
	v_mfma_f32_16x16x32_bf16 v[40:43], v[174:177], v[220:223], v[40:43]
	v_mfma_f32_16x16x32_bf16 v[36:39], v[204:207], v[220:223], v[36:39]
	v_mfma_f32_16x16x32_bf16 v[24:27], v[174:177], v[228:231], v[24:27]
	v_mfma_f32_16x16x32_bf16 v[20:23], v[204:207], v[228:231], v[20:23]
	v_mfma_f32_16x16x32_bf16 v[8:11], v[174:177], v[236:239], v[8:11]
	v_mfma_f32_16x16x32_bf16 v[4:7], v[204:207], v[236:239], v[4:7]
	s_setprio 3
	s_barrier
	s_add_i32 s37, 0, 0x18000
	s_add_i32 s39, 0, 0x1c000
	ds_read_b128 v[158:161], v243 offset:49152
	ds_read_b128 v[174:177], v243 offset:50176
	ds_read_b128 v[180:183], v243 offset:51200
	ds_read_b128 v[204:207], v243 offset:52224
	s_add_u32 s40, s46, 0x80000
	s_addc_u32 s41, s47, 0
	s_mov_b32 m0, s57
	ds_read_b128 v[208:211], v179 offset:32768
	ds_read_b128 v[212:215], v179 offset:33792
	ds_read_b128 v[216:219], v179 offset:34816
	ds_read_b128 v[220:223], v179 offset:35840
	ds_read_b128 v[224:227], v179 offset:36864
	ds_read_b128 v[228:231], v179 offset:37888
	ds_read_b128 v[232:235], v179 offset:38912
	ds_read_b128 v[236:239], v179 offset:39936
	global_load_lds_dwordx4 v2, s[40:41]
	s_mov_b32 m0, s58
	s_nop 0
	global_load_lds_dwordx4 v132, s[40:41]
	s_waitcnt vmcnt(8) lgkmcnt(0)
	s_barrier
; #define PG8_STAGE(bufoff, gbase, voff) do { _Pragma("unroll") for (int _i = 0; _i < 2; ++_i) \
;         __builtin_amdgcn_global_load_lds((const unsigned*)((const char*)(gbase) + (voff)[_i]), (PG8_LAS unsigned*)(lds + (bufoff) + ldsw + _i * 8192), 16, 0, 0); } while (0)
; #define PG8_LDA(dst, b, h) do { _Pragma("unroll") for (int m = 0; m < 4; ++m) _Pragma("unroll") for (int k = 0; k < 2; ++k) dst[m][k] = *(const PG8_LAS bf16x8*)(lds + PG8_SA(b, h) + aoff + m * 2048 + k * 1024); } while (0)
; #define PG8_MMA(ai, bj, At, Bt) do { __builtin_amdgcn_s_setprio(1); _Pragma("unroll") for (int m = 0; m < 4; ++m) _Pragma("unroll") for (int n = 0; n < 2; ++n) _Pragma("unroll") for (int k = 0; k < 2; ++k) \
;         acc[ai][bj][m][n] = __builtin_amdgcn_mfma_f32_16x16x32_bf16(Bt[n][k], At[m][k], acc[ai][bj][m][n], 0, 0, 0); __builtin_amdgcn_s_setprio(0); } while (0)
; #define PG8_WAIT_V(n) asm volatile("s_waitcnt vmcnt(" #n ")" ::: "memory")
; #define PG8_WAIT_L(n) asm volatile("s_waitcnt lgkmcnt(" #n ")" ::: "memory")
; #define PG8_BAR __builtin_amdgcn_s_barrier()
; #define PG8_SCHED __builtin_amdgcn_sched_barrier(0)
; template <class Epi, class Sched, bool ALIGN_EPI = false, bool SP2 = false>
; __device__ __forceinline__ void gemm_phase(PG8_LAS unsigned char* lds, const Gemm g, const Sched& S, const Epi& E) {
;     ...
;             PG8_WAIT_V(8); PG8_WAIT_L(0); PG8_BAR; PG8_MMA(0, 0, At, B0); PG8_MMA(0, 1, At, B1); PG8_BAR; PG8_SCHED;
;             PG8_LDA(At, 1, 1); PG8_STAGE(PG8_SB(1, 0), b3, voffB); PG8_STAGE(PG8_SB(1, 1), b3 + hstep, voffB); PG8_STAGE(PG8_SA(1, 0), a3, voffA);
;             PG8_WAIT_V(8); PG8_WAIT_L(0); PG8_BAR; PG8_MMA(1, 0, At, B0); PG8_MMA(1, 1, At, B1); PG8_BAR; PG8_SCHED;
	s_setprio 0
	s_waitcnt lgkmcnt(0)
	v_mfma_f32_16x16x32_bf16 v[128:131], v[142:145], v[208:211], v[128:131]
	v_mfma_f32_16x16x32_bf16 v[124:127], v[150:153], v[208:211], v[124:127]
	v_mfma_f32_16x16x32_bf16 v[112:115], v[142:145], v[216:219], v[112:115]
	v_mfma_f32_16x16x32_bf16 v[108:111], v[150:153], v[216:219], v[108:111]
	v_mfma_f32_16x16x32_bf16 v[96:99], v[142:145], v[224:227], v[96:99]
	v_mfma_f32_16x16x32_bf16 v[92:95], v[150:153], v[224:227], v[92:95]
	v_mfma_f32_16x16x32_bf16 v[80:83], v[142:145], v[232:235], v[80:83]
	v_mfma_f32_16x16x32_bf16 v[76:79], v[150:153], v[232:235], v[76:79]
	v_mfma_f32_16x16x32_bf16 v[128:131], v[146:149], v[212:215], v[128:131]
	v_mfma_f32_16x16x32_bf16 v[124:127], v[154:157], v[212:215], v[124:127]
	v_mfma_f32_16x16x32_bf16 v[112:115], v[146:149], v[220:223], v[112:115]
	v_mfma_f32_16x16x32_bf16 v[108:111], v[154:157], v[220:223], v[108:111]
	v_mfma_f32_16x16x32_bf16 v[96:99], v[146:149], v[228:231], v[96:99]
	v_mfma_f32_16x16x32_bf16 v[92:95], v[154:157], v[228:231], v[92:95]
	v_mfma_f32_16x16x32_bf16 v[80:83], v[146:149], v[236:239], v[80:83]
	v_mfma_f32_16x16x32_bf16 v[76:79], v[154:157], v[236:239], v[76:79]
	v_mfma_f32_16x16x32_bf16 v[120:123], v[158:161], v[208:211], v[120:123]
	v_mfma_f32_16x16x32_bf16 v[116:119], v[180:183], v[208:211], v[116:119]
	v_mfma_f32_16x16x32_bf16 v[104:107], v[158:161], v[216:219], v[104:107]
	v_mfma_f32_16x16x32_bf16 v[100:103], v[180:183], v[216:219], v[100:103]
	v_mfma_f32_16x16x32_bf16 v[88:91], v[158:161], v[224:227], v[88:91]
	v_mfma_f32_16x16x32_bf16 v[84:87], v[180:183], v[224:227], v[84:87]
	v_mfma_f32_16x16x32_bf16 v[72:75], v[158:161], v[232:235], v[72:75]
	v_mfma_f32_16x16x32_bf16 v[68:71], v[180:183], v[232:235], v[68:71]
	v_mfma_f32_16x16x32_bf16 v[120:123], v[174:177], v[212:215], v[120:123]
	v_mfma_f32_16x16x32_bf16 v[116:119], v[204:207], v[212:215], v[116:119]
	v_mfma_f32_16x16x32_bf16 v[104:107], v[174:177], v[220:223], v[104:107]
	v_mfma_f32_16x16x32_bf16 v[100:103], v[204:207], v[220:223], v[100:103]
	v_mfma_f32_16x16x32_bf16 v[88:91], v[174:177], v[228:231], v[88:91]
	v_mfma_f32_16x16x32_bf16 v[84:87], v[204:207], v[228:231], v[84:87]
	v_mfma_f32_16x16x32_bf16 v[72:75], v[174:177], v[236:239], v[72:75]
	v_mfma_f32_16x16x32_bf16 v[68:71], v[204:207], v[236:239], v[68:71]
	s_setprio 3
	s_barrier
	s_add_i32 s37, s37, s54
	s_add_i32 m0, s37, 0xffffff80
	ds_read_b128 v[208:211], v179 offset:49152
	ds_read_b128 v[212:215], v179 offset:50176
	ds_read_b128 v[216:219], v179 offset:51200
	ds_read_b128 v[220:223], v179 offset:52224
	ds_read_b128 v[224:227], v179 offset:53248
	ds_read_b128 v[228:231], v179 offset:54272
	ds_read_b128 v[232:235], v179 offset:55296
	ds_read_b128 v[236:239], v179 offset:56320
	global_load_lds_dwordx4 v2, s[44:45] offset:128
	s_add_i32 m0, s37, 0x1f80
	s_add_u32 s40, s44, 0x80080
	s_addc_u32 s41, s45, 0
	s_add_i32 s37, s39, s54
	global_load_lds_dwordx4 v132, s[44:45] offset:128
	s_mov_b32 m0, s37
	s_nop 0
	global_load_lds_dwordx4 v2, s[40:41]
	s_add_i32 m0, s37, 0x2000
	s_nop 0
	global_load_lds_dwordx4 v132, s[40:41]
	s_add_i32 m0, s60, 0xffffff80
	s_nop 0
	global_load_lds_dwordx4 v2, s[46:47] offset:128
	s_add_i32 m0, s61, 0xffffff80
	s_nop 0
	global_load_lds_dwordx4 v132, s[46:47] offset:128
	s_waitcnt vmcnt(8) lgkmcnt(0)
	s_barrier
	s_setprio 0
	s_waitcnt lgkmcnt(0)
	v_mfma_f32_16x16x32_bf16 v[64:67], v[142:145], v[208:211], v[64:67]
	v_mfma_f32_16x16x32_bf16 v[60:63], v[150:153], v[208:211], v[60:63]
	v_mfma_f32_16x16x32_bf16 v[48:51], v[142:145], v[216:219], v[48:51]
	v_mfma_f32_16x16x32_bf16 v[44:47], v[150:153], v[216:219], v[44:47]
	v_mfma_f32_16x16x32_bf16 v[32:35], v[142:145], v[224:227], v[32:35]
	v_mfma_f32_16x16x32_bf16 v[28:31], v[150:153], v[224:227], v[28:31]
	v_mfma_f32_16x16x32_bf16 v[16:19], v[142:145], v[232:235], v[16:19]
	v_mfma_f32_16x16x32_bf16 v[12:15], v[150:153], v[232:235], v[12:15]
	v_mfma_f32_16x16x32_bf16 v[64:67], v[146:149], v[212:215], v[64:67]
	v_mfma_f32_16x16x32_bf16 v[60:63], v[154:157], v[212:215], v[60:63]
	v_mfma_f32_16x16x32_bf16 v[48:51], v[146:149], v[220:223], v[48:51]
	v_mfma_f32_16x16x32_bf16 v[44:47], v[154:157], v[220:223], v[44:47]
	v_mfma_f32_16x16x32_bf16 v[32:35], v[146:149], v[228:231], v[32:35]
	v_mfma_f32_16x16x32_bf16 v[28:31], v[154:157], v[228:231], v[28:31]
	v_mfma_f32_16x16x32_bf16 v[16:19], v[146:149], v[236:239], v[16:19]
	v_mfma_f32_16x16x32_bf16 v[12:15], v[154:157], v[236:239], v[12:15]
	v_mfma_f32_16x16x32_bf16 v[56:59], v[158:161], v[208:211], v[56:59]
	ds_read_b128 v[142:145], v243
	v_mfma_f32_16x16x32_bf16 v[52:55], v[180:183], v[208:211], v[52:55]
	ds_read_b128 v[146:149], v243 offset:1024
	v_mfma_f32_16x16x32_bf16 v[40:43], v[158:161], v[216:219], v[40:43]
	ds_read_b128 v[150:153], v243 offset:2048
	v_mfma_f32_16x16x32_bf16 v[36:39], v[180:183], v[216:219], v[36:39]
	ds_read_b128 v[154:157], v243 offset:3072
	v_mfma_f32_16x16x32_bf16 v[24:27], v[158:161], v[224:227], v[24:27]
	v_mfma_f32_16x16x32_bf16 v[20:23], v[180:183], v[224:227], v[20:23]
	v_mfma_f32_16x16x32_bf16 v[8:11], v[158:161], v[232:235], v[8:11]
	v_mfma_f32_16x16x32_bf16 v[4:7], v[180:183], v[232:235], v[4:7]
	v_mfma_f32_16x16x32_bf16 v[56:59], v[174:177], v[212:215], v[56:59]
	v_mfma_f32_16x16x32_bf16 v[52:55], v[204:207], v[212:215], v[52:55]
	v_mfma_f32_16x16x32_bf16 v[40:43], v[174:177], v[220:223], v[40:43]
	v_mfma_f32_16x16x32_bf16 v[36:39], v[204:207], v[220:223], v[36:39]
	v_mfma_f32_16x16x32_bf16 v[24:27], v[174:177], v[228:231], v[24:27]
	v_mfma_f32_16x16x32_bf16 v[20:23], v[204:207], v[228:231], v[20:23]
	v_mfma_f32_16x16x32_bf16 v[8:11], v[174:177], v[236:239], v[8:11]
	v_mfma_f32_16x16x32_bf16 v[4:7], v[204:207], v[236:239], v[4:7]
	s_setprio 3
	s_barrier
	s_add_i32 s31, s31, 2
	s_add_u32 s2, s2, 0x100
	s_addc_u32 s29, s29, 0
	s_cmp_gt_u32 s31, 29
	s_mov_b64 s[40:41], s[42:43]
	s_cbranch_scc0 .LBB0_2185
	s_and_b64 vcc, exec, s[26:27]
	s_cbranch_vccz .LBB0_2188
	s_barrier
